# K loops: removed the s_nop placeholders of the former s_setprio pairs and the redundant post-barrier lgkmcnt wait
# speedup vs baseline: 1.0056x; 1.0024x over previous
.Lsp_p1:
.LBB0_277:
	ds_read_b128 v[148:151], v145
	ds_read_b128 v[152:155], v145 offset:1024
	ds_read_b128 v[156:159], v145 offset:2048
	ds_read_b128 v[160:163], v145 offset:3072
	ds_read_b128 v[166:169], v146
	ds_read_b128 v[170:173], v146 offset:1024
	ds_read_b128 v[174:177], v146 offset:2048
	ds_read_b128 v[178:181], v146 offset:3072
	s_add_u32 s28, s26, 0xfff80080
	s_addc_u32 s29, s27, -1
	s_cmp_eq_u32 s50, 28
	s_cselect_b32 s31, s2, s29
	s_cselect_b32 s30, s13, s28
	s_cselect_b32 s29, s15, s33
	s_cselect_b32 s28, s23, s25
	v_lshl_add_u64 v[214:215], s[26:27], 0, v[138:139]
	s_add_i32 m0, s37, 0xc000
	ds_read_b128 v[182:185], v147
	ds_read_b128 v[186:189], v147 offset:1024
	ds_read_b128 v[190:193], v147 offset:2048
	ds_read_b128 v[194:197], v147 offset:3072
	ds_read_b128 v[198:201], v147 offset:4096
	ds_read_b128 v[202:205], v147 offset:5120
	ds_read_b128 v[206:209], v147 offset:6144
	ds_read_b128 v[210:213], v147 offset:7168
	global_load_lds_dwordx4 v[214:215], off
	v_lshl_add_u64 v[214:215], s[26:27], 0, v[140:141]
	s_add_i32 m0, s37, 0xe000
	s_nop 0
	global_load_lds_dwordx4 v[214:215], off
	s_waitcnt vmcnt(8)
	s_waitcnt lgkmcnt(0)
	s_barrier
	v_mfma_f32_16x16x32_bf16 v[126:129], v[148:151], v[182:185], v[126:129]
	v_mfma_f32_16x16x32_bf16 v[122:125], v[156:159], v[182:185], v[122:125]
	v_mfma_f32_16x16x32_bf16 v[110:113], v[148:151], v[190:193], v[110:113]
	v_mfma_f32_16x16x32_bf16 v[106:109], v[156:159], v[190:193], v[106:109]
	v_mfma_f32_16x16x32_bf16 v[94:97], v[148:151], v[198:201], v[94:97]
	v_mfma_f32_16x16x32_bf16 v[90:93], v[156:159], v[198:201], v[90:93]
	v_mfma_f32_16x16x32_bf16 v[78:81], v[148:151], v[206:209], v[78:81]
	v_mfma_f32_16x16x32_bf16 v[74:77], v[156:159], v[206:209], v[74:77]
	v_mfma_f32_16x16x32_bf16 v[126:129], v[152:155], v[186:189], v[126:129]
	v_mfma_f32_16x16x32_bf16 v[122:125], v[160:163], v[186:189], v[122:125]
	v_mfma_f32_16x16x32_bf16 v[110:113], v[152:155], v[194:197], v[110:113]
	v_mfma_f32_16x16x32_bf16 v[106:109], v[160:163], v[194:197], v[106:109]
	v_mfma_f32_16x16x32_bf16 v[94:97], v[152:155], v[202:205], v[94:97]
	v_mfma_f32_16x16x32_bf16 v[90:93], v[160:163], v[202:205], v[90:93]
	v_mfma_f32_16x16x32_bf16 v[78:81], v[152:155], v[210:213], v[78:81]
	v_mfma_f32_16x16x32_bf16 v[74:77], v[160:163], v[210:213], v[74:77]
	v_mfma_f32_16x16x32_bf16 v[118:121], v[166:169], v[182:185], v[118:121]
	v_mfma_f32_16x16x32_bf16 v[114:117], v[174:177], v[182:185], v[114:117]
	v_mfma_f32_16x16x32_bf16 v[102:105], v[166:169], v[190:193], v[102:105]
	v_mfma_f32_16x16x32_bf16 v[98:101], v[174:177], v[190:193], v[98:101]
	v_mfma_f32_16x16x32_bf16 v[86:89], v[166:169], v[198:201], v[86:89]
	v_mfma_f32_16x16x32_bf16 v[82:85], v[174:177], v[198:201], v[82:85]
	v_mfma_f32_16x16x32_bf16 v[70:73], v[166:169], v[206:209], v[70:73]
	v_mfma_f32_16x16x32_bf16 v[66:69], v[174:177], v[206:209], v[66:69]
	v_mfma_f32_16x16x32_bf16 v[118:121], v[170:173], v[186:189], v[118:121]
	v_mfma_f32_16x16x32_bf16 v[114:117], v[178:181], v[186:189], v[114:117]
	v_mfma_f32_16x16x32_bf16 v[102:105], v[170:173], v[194:197], v[102:105]
	v_mfma_f32_16x16x32_bf16 v[98:101], v[178:181], v[194:197], v[98:101]
	v_mfma_f32_16x16x32_bf16 v[86:89], v[170:173], v[202:205], v[86:89]
	v_mfma_f32_16x16x32_bf16 v[82:85], v[178:181], v[202:205], v[82:85]
	v_mfma_f32_16x16x32_bf16 v[70:73], v[170:173], v[210:213], v[70:73]
	v_mfma_f32_16x16x32_bf16 v[66:69], v[178:181], v[210:213], v[66:69]
	s_barrier
	s_add_i32 s51, s48, s36
	v_lshl_add_u64 v[214:215], s[28:29], 0, v[132:133]
	s_mov_b32 m0, s51
	ds_read_b128 v[182:185], v147 offset:16384
	ds_read_b128 v[186:189], v147 offset:17408
	ds_read_b128 v[190:193], v147 offset:18432
	ds_read_b128 v[194:197], v147 offset:19456
	ds_read_b128 v[198:201], v147 offset:20480
	ds_read_b128 v[202:205], v147 offset:21504
	ds_read_b128 v[206:209], v147 offset:22528
	ds_read_b128 v[210:213], v147 offset:23552
	global_load_lds_dwordx4 v[214:215], off
	s_add_i32 m0, s51, 0x2000
	s_add_u32 s52, s28, 0x80000
	v_lshl_add_u64 v[216:217], s[28:29], 0, v[136:137]
	s_addc_u32 s53, s29, 0
	s_add_i32 s51, s49, s36
	global_load_lds_dwordx4 v[216:217], off
	v_lshl_add_u64 v[218:219], s[52:53], 0, v[132:133]
	s_mov_b32 m0, s51
	v_lshl_add_u64 v[220:221], s[30:31], 0, v[134:135]
	global_load_lds_dwordx4 v[218:219], off
	v_lshl_add_u64 v[218:219], s[52:53], 0, v[136:137]
	s_add_i32 m0, s51, 0x2000
	s_nop 0
	global_load_lds_dwordx4 v[218:219], off
	v_lshl_add_u64 v[218:219], s[30:31], 0, v[130:131]
	s_mov_b32 m0, s37
	s_nop 0
	global_load_lds_dwordx4 v[218:219], off
	s_mov_b32 m0, s38
	s_nop 0
	global_load_lds_dwordx4 v[220:221], off
	s_waitcnt vmcnt(8)
	s_waitcnt lgkmcnt(0)
	s_barrier
	v_mfma_f32_16x16x32_bf16 v[62:65], v[148:151], v[182:185], v[62:65]
	v_mfma_f32_16x16x32_bf16 v[58:61], v[156:159], v[182:185], v[58:61]
	v_mfma_f32_16x16x32_bf16 v[46:49], v[148:151], v[190:193], v[46:49]
	v_mfma_f32_16x16x32_bf16 v[42:45], v[156:159], v[190:193], v[42:45]
	v_mfma_f32_16x16x32_bf16 v[30:33], v[148:151], v[198:201], v[30:33]
	v_mfma_f32_16x16x32_bf16 v[26:29], v[156:159], v[198:201], v[26:29]
	v_mfma_f32_16x16x32_bf16 v[14:17], v[148:151], v[206:209], v[14:17]
	v_mfma_f32_16x16x32_bf16 v[10:13], v[156:159], v[206:209], v[10:13]
	v_mfma_f32_16x16x32_bf16 v[62:65], v[152:155], v[186:189], v[62:65]
	v_mfma_f32_16x16x32_bf16 v[58:61], v[160:163], v[186:189], v[58:61]
	v_mfma_f32_16x16x32_bf16 v[46:49], v[152:155], v[194:197], v[46:49]
	v_mfma_f32_16x16x32_bf16 v[42:45], v[160:163], v[194:197], v[42:45]
	v_mfma_f32_16x16x32_bf16 v[30:33], v[152:155], v[202:205], v[30:33]
	v_mfma_f32_16x16x32_bf16 v[26:29], v[160:163], v[202:205], v[26:29]
	v_mfma_f32_16x16x32_bf16 v[14:17], v[152:155], v[210:213], v[14:17]
	v_mfma_f32_16x16x32_bf16 v[10:13], v[160:163], v[210:213], v[10:13]
	v_mfma_f32_16x16x32_bf16 v[54:57], v[166:169], v[182:185], v[54:57]
	v_mfma_f32_16x16x32_bf16 v[50:53], v[174:177], v[182:185], v[50:53]
	v_mfma_f32_16x16x32_bf16 v[38:41], v[166:169], v[190:193], v[38:41]
	v_mfma_f32_16x16x32_bf16 v[34:37], v[174:177], v[190:193], v[34:37]
	v_mfma_f32_16x16x32_bf16 v[22:25], v[166:169], v[198:201], v[22:25]
	v_mfma_f32_16x16x32_bf16 v[18:21], v[174:177], v[198:201], v[18:21]
	v_mfma_f32_16x16x32_bf16 v[6:9], v[166:169], v[206:209], v[6:9]
	v_mfma_f32_16x16x32_bf16 v[2:5], v[174:177], v[206:209], v[2:5]
	v_mfma_f32_16x16x32_bf16 v[54:57], v[170:173], v[186:189], v[54:57]
	v_mfma_f32_16x16x32_bf16 v[50:53], v[178:181], v[186:189], v[50:53]
	v_mfma_f32_16x16x32_bf16 v[38:41], v[170:173], v[194:197], v[38:41]
	v_mfma_f32_16x16x32_bf16 v[34:37], v[178:181], v[194:197], v[34:37]
	v_mfma_f32_16x16x32_bf16 v[22:25], v[170:173], v[202:205], v[22:25]
	v_mfma_f32_16x16x32_bf16 v[18:21], v[178:181], v[202:205], v[18:21]
	v_mfma_f32_16x16x32_bf16 v[6:9], v[170:173], v[210:213], v[6:9]
	v_mfma_f32_16x16x32_bf16 v[2:5], v[178:181], v[210:213], v[2:5]
	s_barrier
	s_add_i32 s51, 0, 0x18000
	s_add_i32 s52, 0, 0x1c000
	v_add_u32_e32 v160, s51, v144
	v_add_u32_e32 v164, s52, v144
	ds_read_b128 v[148:151], v160
	ds_read_b128 v[152:155], v160 offset:1024
	ds_read_b128 v[156:159], v160 offset:2048
	ds_read_b128 v[160:163], v160 offset:3072
	ds_read_b128 v[166:169], v164
	ds_read_b128 v[170:173], v164 offset:1024
	ds_read_b128 v[174:177], v164 offset:2048
	ds_read_b128 v[178:181], v164 offset:3072
	s_add_u32 s30, s30, 0x80000
	s_addc_u32 s31, s31, 0
	s_mov_b32 m0, s39
	v_lshl_add_u64 v[222:223], s[30:31], 0, v[130:131]
	ds_read_b128 v[182:185], v147 offset:32768
	ds_read_b128 v[186:189], v147 offset:33792
	ds_read_b128 v[190:193], v147 offset:34816
	ds_read_b128 v[194:197], v147 offset:35840
	ds_read_b128 v[198:201], v147 offset:36864
	ds_read_b128 v[202:205], v147 offset:37888
	ds_read_b128 v[206:209], v147 offset:38912
	ds_read_b128 v[210:213], v147 offset:39936
	global_load_lds_dwordx4 v[222:223], off
	v_lshl_add_u64 v[222:223], s[30:31], 0, v[134:135]
	s_mov_b32 m0, s40
	s_nop 0
	global_load_lds_dwordx4 v[222:223], off
	s_waitcnt vmcnt(8)
	s_waitcnt lgkmcnt(0)
	s_barrier
	v_mfma_f32_16x16x32_bf16 v[126:129], v[148:151], v[182:185], v[126:129]
	v_mfma_f32_16x16x32_bf16 v[122:125], v[156:159], v[182:185], v[122:125]
	v_mfma_f32_16x16x32_bf16 v[110:113], v[148:151], v[190:193], v[110:113]
	v_mfma_f32_16x16x32_bf16 v[106:109], v[156:159], v[190:193], v[106:109]
	v_mfma_f32_16x16x32_bf16 v[94:97], v[148:151], v[198:201], v[94:97]
	v_mfma_f32_16x16x32_bf16 v[90:93], v[156:159], v[198:201], v[90:93]
	v_mfma_f32_16x16x32_bf16 v[78:81], v[148:151], v[206:209], v[78:81]
	v_mfma_f32_16x16x32_bf16 v[74:77], v[156:159], v[206:209], v[74:77]
	v_mfma_f32_16x16x32_bf16 v[126:129], v[152:155], v[186:189], v[126:129]
	v_mfma_f32_16x16x32_bf16 v[122:125], v[160:163], v[186:189], v[122:125]
	v_mfma_f32_16x16x32_bf16 v[110:113], v[152:155], v[194:197], v[110:113]
	v_mfma_f32_16x16x32_bf16 v[106:109], v[160:163], v[194:197], v[106:109]
	v_mfma_f32_16x16x32_bf16 v[94:97], v[152:155], v[202:205], v[94:97]
	v_mfma_f32_16x16x32_bf16 v[90:93], v[160:163], v[202:205], v[90:93]
	v_mfma_f32_16x16x32_bf16 v[78:81], v[152:155], v[210:213], v[78:81]
	v_mfma_f32_16x16x32_bf16 v[74:77], v[160:163], v[210:213], v[74:77]
	v_mfma_f32_16x16x32_bf16 v[118:121], v[166:169], v[182:185], v[118:121]
	v_mfma_f32_16x16x32_bf16 v[114:117], v[174:177], v[182:185], v[114:117]
	v_mfma_f32_16x16x32_bf16 v[102:105], v[166:169], v[190:193], v[102:105]
	v_mfma_f32_16x16x32_bf16 v[98:101], v[174:177], v[190:193], v[98:101]
	v_mfma_f32_16x16x32_bf16 v[86:89], v[166:169], v[198:201], v[86:89]
	v_mfma_f32_16x16x32_bf16 v[82:85], v[174:177], v[198:201], v[82:85]
	v_mfma_f32_16x16x32_bf16 v[70:73], v[166:169], v[206:209], v[70:73]
	v_mfma_f32_16x16x32_bf16 v[66:69], v[174:177], v[206:209], v[66:69]
	v_mfma_f32_16x16x32_bf16 v[118:121], v[170:173], v[186:189], v[118:121]
	v_mfma_f32_16x16x32_bf16 v[114:117], v[178:181], v[186:189], v[114:117]
	v_mfma_f32_16x16x32_bf16 v[102:105], v[170:173], v[194:197], v[102:105]
	v_mfma_f32_16x16x32_bf16 v[98:101], v[178:181], v[194:197], v[98:101]
	v_mfma_f32_16x16x32_bf16 v[86:89], v[170:173], v[202:205], v[86:89]
	v_mfma_f32_16x16x32_bf16 v[82:85], v[178:181], v[202:205], v[82:85]
	v_mfma_f32_16x16x32_bf16 v[70:73], v[170:173], v[210:213], v[70:73]
	v_mfma_f32_16x16x32_bf16 v[66:69], v[178:181], v[210:213], v[66:69]
	s_barrier
	s_add_i32 s30, s51, s36
	v_lshl_add_u64 v[214:215], v[214:215], 0, s[8:9]
	s_mov_b32 m0, s30
	ds_read_b128 v[182:185], v147 offset:49152
	ds_read_b128 v[186:189], v147 offset:50176
	ds_read_b128 v[190:193], v147 offset:51200
	ds_read_b128 v[194:197], v147 offset:52224
	ds_read_b128 v[198:201], v147 offset:53248
	ds_read_b128 v[202:205], v147 offset:54272
	ds_read_b128 v[206:209], v147 offset:55296
	ds_read_b128 v[210:213], v147 offset:56320
	global_load_lds_dwordx4 v[214:215], off
	s_add_i32 m0, s30, 0x2000
	s_add_u32 s28, s28, 0x80080
	v_lshl_add_u64 v[214:215], v[216:217], 0, s[8:9]
	s_addc_u32 s29, s29, 0
	s_add_i32 s30, s52, s36
	global_load_lds_dwordx4 v[214:215], off
	v_lshl_add_u64 v[214:215], s[28:29], 0, v[132:133]
	s_mov_b32 m0, s30
	s_nop 0
	global_load_lds_dwordx4 v[214:215], off
	v_lshl_add_u64 v[214:215], s[28:29], 0, v[136:137]
	s_add_i32 m0, s30, 0x2000
	s_nop 0
	global_load_lds_dwordx4 v[214:215], off
	v_lshl_add_u64 v[214:215], v[218:219], 0, s[8:9]
	s_mov_b32 m0, s44
	s_nop 0
	global_load_lds_dwordx4 v[214:215], off
	v_lshl_add_u64 v[214:215], v[220:221], 0, s[8:9]
	s_mov_b32 m0, s45
	s_nop 0
	global_load_lds_dwordx4 v[214:215], off
	s_waitcnt vmcnt(8)
	s_waitcnt lgkmcnt(0)
	s_barrier
	v_mfma_f32_16x16x32_bf16 v[62:65], v[148:151], v[182:185], v[62:65]
	v_mfma_f32_16x16x32_bf16 v[58:61], v[156:159], v[182:185], v[58:61]
	v_mfma_f32_16x16x32_bf16 v[46:49], v[148:151], v[190:193], v[46:49]
	v_mfma_f32_16x16x32_bf16 v[42:45], v[156:159], v[190:193], v[42:45]
	v_mfma_f32_16x16x32_bf16 v[30:33], v[148:151], v[198:201], v[30:33]
	v_mfma_f32_16x16x32_bf16 v[26:29], v[156:159], v[198:201], v[26:29]
	v_mfma_f32_16x16x32_bf16 v[14:17], v[148:151], v[206:209], v[14:17]
	v_mfma_f32_16x16x32_bf16 v[10:13], v[156:159], v[206:209], v[10:13]
	v_mfma_f32_16x16x32_bf16 v[62:65], v[152:155], v[186:189], v[62:65]
	v_mfma_f32_16x16x32_bf16 v[58:61], v[160:163], v[186:189], v[58:61]
	v_mfma_f32_16x16x32_bf16 v[46:49], v[152:155], v[194:197], v[46:49]
	v_mfma_f32_16x16x32_bf16 v[42:45], v[160:163], v[194:197], v[42:45]
	v_mfma_f32_16x16x32_bf16 v[30:33], v[152:155], v[202:205], v[30:33]
	v_mfma_f32_16x16x32_bf16 v[26:29], v[160:163], v[202:205], v[26:29]
	v_mfma_f32_16x16x32_bf16 v[14:17], v[152:155], v[210:213], v[14:17]
	v_mfma_f32_16x16x32_bf16 v[10:13], v[160:163], v[210:213], v[10:13]
	v_mfma_f32_16x16x32_bf16 v[54:57], v[166:169], v[182:185], v[54:57]
	v_mfma_f32_16x16x32_bf16 v[50:53], v[174:177], v[182:185], v[50:53]
	v_mfma_f32_16x16x32_bf16 v[38:41], v[166:169], v[190:193], v[38:41]
	v_mfma_f32_16x16x32_bf16 v[34:37], v[174:177], v[190:193], v[34:37]
	v_mfma_f32_16x16x32_bf16 v[22:25], v[166:169], v[198:201], v[22:25]
	v_mfma_f32_16x16x32_bf16 v[18:21], v[174:177], v[198:201], v[18:21]
	v_mfma_f32_16x16x32_bf16 v[6:9], v[166:169], v[206:209], v[6:9]
	v_mfma_f32_16x16x32_bf16 v[2:5], v[174:177], v[206:209], v[2:5]
	v_mfma_f32_16x16x32_bf16 v[54:57], v[170:173], v[186:189], v[54:57]
	v_mfma_f32_16x16x32_bf16 v[50:53], v[178:181], v[186:189], v[50:53]
	v_mfma_f32_16x16x32_bf16 v[38:41], v[170:173], v[194:197], v[38:41]
	v_mfma_f32_16x16x32_bf16 v[34:37], v[178:181], v[194:197], v[34:37]
	v_mfma_f32_16x16x32_bf16 v[22:25], v[170:173], v[202:205], v[22:25]
	v_mfma_f32_16x16x32_bf16 v[18:21], v[178:181], v[202:205], v[18:21]
	v_mfma_f32_16x16x32_bf16 v[6:9], v[170:173], v[210:213], v[6:9]
	v_mfma_f32_16x16x32_bf16 v[2:5], v[178:181], v[210:213], v[2:5]
	s_barrier
	s_add_i32 s50, s50, 2
	s_add_u32 s26, s26, 0x100
	s_addc_u32 s27, s27, 0
	s_add_u32 s25, s25, 0x100
	s_addc_u32 s33, s33, 0
	s_cmp_gt_u32 s50, 29
	s_cbranch_scc0 .LBB0_277
	s_setprio 0
	s_and_b64 vcc, exec, s[10:11]
	s_cbranch_vccz .LBB0_280
	s_barrier

.Lsp_p4:
.LBB0_704:
	ds_read_b128 v[144:147], v152
	ds_read_b128 v[156:159], v152 offset:1024
	ds_read_b128 v[160:163], v152 offset:2048
	ds_read_b128 v[166:169], v152 offset:3072
	ds_read_b128 v[170:173], v153
	ds_read_b128 v[174:177], v153 offset:1024
	ds_read_b128 v[178:181], v153 offset:2048
	ds_read_b128 v[182:185], v153 offset:3072
	s_add_u32 s24, s22, 0xfff80080
	s_addc_u32 s25, s23, -1
	s_cmp_eq_u32 s45, 28
	s_cselect_b32 s27, s17, s25
	s_cselect_b32 s26, s16, s24
	s_cselect_b32 s25, s21, s15
	s_cselect_b32 s24, s20, s5
	s_mov_b32 m0, s42
	v_lshl_add_u64 v[218:219], s[22:23], 0, v[140:141]
	ds_read_b128 v[186:189], v154
	ds_read_b128 v[190:193], v154 offset:1024
	ds_read_b128 v[194:197], v154 offset:2048
	ds_read_b128 v[198:201], v154 offset:3072
	ds_read_b128 v[202:205], v154 offset:4096
	ds_read_b128 v[206:209], v154 offset:5120
	ds_read_b128 v[210:213], v154 offset:6144
	ds_read_b128 v[214:217], v154 offset:7168
	global_load_lds_dwordx4 v[218:219], off
	v_lshl_add_u64 v[218:219], s[22:23], 0, v[142:143]
	s_add_i32 m0, s30, 0xe000
	s_nop 0
	global_load_lds_dwordx4 v[218:219], off
	s_waitcnt vmcnt(8)
	s_waitcnt lgkmcnt(0)
	s_barrier
	v_mfma_f32_16x16x32_bf16 v[126:129], v[144:147], v[186:189], v[126:129]
	v_mfma_f32_16x16x32_bf16 v[122:125], v[160:163], v[186:189], v[122:125]
	v_mfma_f32_16x16x32_bf16 v[110:113], v[144:147], v[194:197], v[110:113]
	v_mfma_f32_16x16x32_bf16 v[106:109], v[160:163], v[194:197], v[106:109]
	v_mfma_f32_16x16x32_bf16 v[94:97], v[144:147], v[202:205], v[94:97]
	v_mfma_f32_16x16x32_bf16 v[90:93], v[160:163], v[202:205], v[90:93]
	v_mfma_f32_16x16x32_bf16 v[78:81], v[144:147], v[210:213], v[78:81]
	v_mfma_f32_16x16x32_bf16 v[74:77], v[160:163], v[210:213], v[74:77]
	v_mfma_f32_16x16x32_bf16 v[126:129], v[156:159], v[190:193], v[126:129]
	v_mfma_f32_16x16x32_bf16 v[122:125], v[166:169], v[190:193], v[122:125]
	v_mfma_f32_16x16x32_bf16 v[110:113], v[156:159], v[198:201], v[110:113]
	v_mfma_f32_16x16x32_bf16 v[106:109], v[166:169], v[198:201], v[106:109]
	v_mfma_f32_16x16x32_bf16 v[94:97], v[156:159], v[206:209], v[94:97]
	v_mfma_f32_16x16x32_bf16 v[90:93], v[166:169], v[206:209], v[90:93]
	v_mfma_f32_16x16x32_bf16 v[78:81], v[156:159], v[214:217], v[78:81]
	v_mfma_f32_16x16x32_bf16 v[74:77], v[166:169], v[214:217], v[74:77]
	v_mfma_f32_16x16x32_bf16 v[118:121], v[170:173], v[186:189], v[118:121]
	v_mfma_f32_16x16x32_bf16 v[114:117], v[178:181], v[186:189], v[114:117]
	v_mfma_f32_16x16x32_bf16 v[102:105], v[170:173], v[194:197], v[102:105]
	v_mfma_f32_16x16x32_bf16 v[98:101], v[178:181], v[194:197], v[98:101]
	v_mfma_f32_16x16x32_bf16 v[86:89], v[170:173], v[202:205], v[86:89]
	v_mfma_f32_16x16x32_bf16 v[82:85], v[178:181], v[202:205], v[82:85]
	v_mfma_f32_16x16x32_bf16 v[70:73], v[170:173], v[210:213], v[70:73]
	v_mfma_f32_16x16x32_bf16 v[66:69], v[178:181], v[210:213], v[66:69]
	v_mfma_f32_16x16x32_bf16 v[118:121], v[174:177], v[190:193], v[118:121]
	v_mfma_f32_16x16x32_bf16 v[114:117], v[182:185], v[190:193], v[114:117]
	v_mfma_f32_16x16x32_bf16 v[102:105], v[174:177], v[198:201], v[102:105]
	v_mfma_f32_16x16x32_bf16 v[98:101], v[182:185], v[198:201], v[98:101]
	v_mfma_f32_16x16x32_bf16 v[86:89], v[174:177], v[206:209], v[86:89]
	v_mfma_f32_16x16x32_bf16 v[82:85], v[182:185], v[206:209], v[82:85]
	v_mfma_f32_16x16x32_bf16 v[70:73], v[174:177], v[214:217], v[70:73]
	v_mfma_f32_16x16x32_bf16 v[66:69], v[182:185], v[214:217], v[66:69]
	s_barrier
	s_add_i32 s46, s40, s29
	v_lshl_add_u64 v[218:219], s[24:25], 0, v[134:135]
	s_mov_b32 m0, s46
	ds_read_b128 v[186:189], v154 offset:16384
	ds_read_b128 v[190:193], v154 offset:17408
	ds_read_b128 v[194:197], v154 offset:18432
	ds_read_b128 v[198:201], v154 offset:19456
	ds_read_b128 v[202:205], v154 offset:20480
	ds_read_b128 v[206:209], v154 offset:21504
	ds_read_b128 v[210:213], v154 offset:22528
	ds_read_b128 v[214:217], v154 offset:23552
	global_load_lds_dwordx4 v[218:219], off
	s_add_i32 m0, s46, 0x2000
	s_add_u32 s46, s24, 0x80000
	v_lshl_add_u64 v[220:221], s[24:25], 0, v[138:139]
	s_addc_u32 s47, s25, 0
	s_add_i32 s48, s41, s29
	global_load_lds_dwordx4 v[220:221], off
	v_lshl_add_u64 v[222:223], s[46:47], 0, v[134:135]
	s_mov_b32 m0, s48
	v_lshl_add_u64 v[224:225], s[26:27], 0, v[136:137]
	global_load_lds_dwordx4 v[222:223], off
	v_lshl_add_u64 v[222:223], s[46:47], 0, v[138:139]
	s_add_i32 m0, s48, 0x2000
	s_nop 0
	global_load_lds_dwordx4 v[222:223], off
	v_lshl_add_u64 v[222:223], s[26:27], 0, v[132:133]
	s_mov_b32 m0, s30
	s_nop 0
	global_load_lds_dwordx4 v[222:223], off
	s_mov_b32 m0, s31
	s_nop 0
	global_load_lds_dwordx4 v[224:225], off
	s_waitcnt vmcnt(8)
	s_waitcnt lgkmcnt(0)
	s_barrier
	v_mfma_f32_16x16x32_bf16 v[62:65], v[144:147], v[186:189], v[62:65]
	v_mfma_f32_16x16x32_bf16 v[58:61], v[160:163], v[186:189], v[58:61]
	v_mfma_f32_16x16x32_bf16 v[46:49], v[144:147], v[194:197], v[46:49]
	v_mfma_f32_16x16x32_bf16 v[42:45], v[160:163], v[194:197], v[42:45]
	v_mfma_f32_16x16x32_bf16 v[30:33], v[144:147], v[202:205], v[30:33]
	v_mfma_f32_16x16x32_bf16 v[26:29], v[160:163], v[202:205], v[26:29]
	v_mfma_f32_16x16x32_bf16 v[14:17], v[144:147], v[210:213], v[14:17]
	v_mfma_f32_16x16x32_bf16 v[10:13], v[160:163], v[210:213], v[10:13]
	v_mfma_f32_16x16x32_bf16 v[62:65], v[156:159], v[190:193], v[62:65]
	v_mfma_f32_16x16x32_bf16 v[58:61], v[166:169], v[190:193], v[58:61]
	v_mfma_f32_16x16x32_bf16 v[46:49], v[156:159], v[198:201], v[46:49]
	v_mfma_f32_16x16x32_bf16 v[42:45], v[166:169], v[198:201], v[42:45]
	v_mfma_f32_16x16x32_bf16 v[30:33], v[156:159], v[206:209], v[30:33]
	v_mfma_f32_16x16x32_bf16 v[26:29], v[166:169], v[206:209], v[26:29]
	v_mfma_f32_16x16x32_bf16 v[14:17], v[156:159], v[214:217], v[14:17]
	v_mfma_f32_16x16x32_bf16 v[10:13], v[166:169], v[214:217], v[10:13]
	v_mfma_f32_16x16x32_bf16 v[54:57], v[170:173], v[186:189], v[54:57]
	v_mfma_f32_16x16x32_bf16 v[50:53], v[178:181], v[186:189], v[50:53]
	v_mfma_f32_16x16x32_bf16 v[38:41], v[170:173], v[194:197], v[38:41]
	v_mfma_f32_16x16x32_bf16 v[34:37], v[178:181], v[194:197], v[34:37]
	v_mfma_f32_16x16x32_bf16 v[22:25], v[170:173], v[202:205], v[22:25]
	v_mfma_f32_16x16x32_bf16 v[18:21], v[178:181], v[202:205], v[18:21]
	v_mfma_f32_16x16x32_bf16 v[6:9], v[170:173], v[210:213], v[6:9]
	v_mfma_f32_16x16x32_bf16 v[2:5], v[178:181], v[210:213], v[2:5]
	v_mfma_f32_16x16x32_bf16 v[54:57], v[174:177], v[190:193], v[54:57]
	v_mfma_f32_16x16x32_bf16 v[50:53], v[182:185], v[190:193], v[50:53]
	v_mfma_f32_16x16x32_bf16 v[38:41], v[174:177], v[198:201], v[38:41]
	v_mfma_f32_16x16x32_bf16 v[34:37], v[182:185], v[198:201], v[34:37]
	v_mfma_f32_16x16x32_bf16 v[22:25], v[174:177], v[206:209], v[22:25]
	v_mfma_f32_16x16x32_bf16 v[18:21], v[182:185], v[206:209], v[18:21]
	v_mfma_f32_16x16x32_bf16 v[6:9], v[174:177], v[214:217], v[6:9]
	v_mfma_f32_16x16x32_bf16 v[2:5], v[182:185], v[214:217], v[2:5]
	s_barrier
	s_add_i32 s46, 0, 0x18000
	v_add_u32_e32 v155, s46, v1
	s_add_i32 s47, 0, 0x1c000
	ds_read_b128 v[144:147], v155
	ds_read_b128 v[156:159], v155 offset:1024
	ds_read_b128 v[160:163], v155 offset:2048
	ds_read_b128 v[166:169], v155 offset:3072
	v_add_u32_e32 v155, s47, v1
	ds_read_b128 v[170:173], v155
	ds_read_b128 v[174:177], v155 offset:1024
	ds_read_b128 v[178:181], v155 offset:2048
	ds_read_b128 v[182:185], v155 offset:3072
	s_add_u32 s26, s26, 0x80000
	s_addc_u32 s27, s27, 0
	s_mov_b32 m0, s33
	v_lshl_add_u64 v[226:227], s[26:27], 0, v[132:133]
	ds_read_b128 v[186:189], v154 offset:32768
	ds_read_b128 v[190:193], v154 offset:33792
	ds_read_b128 v[194:197], v154 offset:34816
	ds_read_b128 v[198:201], v154 offset:35840
	ds_read_b128 v[202:205], v154 offset:36864
	ds_read_b128 v[206:209], v154 offset:37888
	ds_read_b128 v[210:213], v154 offset:38912
	ds_read_b128 v[214:217], v154 offset:39936
	global_load_lds_dwordx4 v[226:227], off
	v_lshl_add_u64 v[226:227], s[26:27], 0, v[136:137]
	s_mov_b32 m0, s34
	s_nop 0
	global_load_lds_dwordx4 v[226:227], off
	s_waitcnt vmcnt(8)
	s_waitcnt lgkmcnt(0)
	s_barrier
	v_mfma_f32_16x16x32_bf16 v[126:129], v[144:147], v[186:189], v[126:129]
	v_mfma_f32_16x16x32_bf16 v[122:125], v[160:163], v[186:189], v[122:125]
	v_mfma_f32_16x16x32_bf16 v[110:113], v[144:147], v[194:197], v[110:113]
	v_mfma_f32_16x16x32_bf16 v[106:109], v[160:163], v[194:197], v[106:109]
	v_mfma_f32_16x16x32_bf16 v[94:97], v[144:147], v[202:205], v[94:97]
	v_mfma_f32_16x16x32_bf16 v[90:93], v[160:163], v[202:205], v[90:93]
	v_mfma_f32_16x16x32_bf16 v[78:81], v[144:147], v[210:213], v[78:81]
	v_mfma_f32_16x16x32_bf16 v[74:77], v[160:163], v[210:213], v[74:77]
	v_mfma_f32_16x16x32_bf16 v[126:129], v[156:159], v[190:193], v[126:129]
	v_mfma_f32_16x16x32_bf16 v[122:125], v[166:169], v[190:193], v[122:125]
	v_mfma_f32_16x16x32_bf16 v[110:113], v[156:159], v[198:201], v[110:113]
	v_mfma_f32_16x16x32_bf16 v[106:109], v[166:169], v[198:201], v[106:109]
	v_mfma_f32_16x16x32_bf16 v[94:97], v[156:159], v[206:209], v[94:97]
	v_mfma_f32_16x16x32_bf16 v[90:93], v[166:169], v[206:209], v[90:93]
	v_mfma_f32_16x16x32_bf16 v[78:81], v[156:159], v[214:217], v[78:81]
	v_mfma_f32_16x16x32_bf16 v[74:77], v[166:169], v[214:217], v[74:77]
	v_mfma_f32_16x16x32_bf16 v[118:121], v[170:173], v[186:189], v[118:121]
	v_mfma_f32_16x16x32_bf16 v[114:117], v[178:181], v[186:189], v[114:117]
	v_mfma_f32_16x16x32_bf16 v[102:105], v[170:173], v[194:197], v[102:105]
	v_mfma_f32_16x16x32_bf16 v[98:101], v[178:181], v[194:197], v[98:101]
	v_mfma_f32_16x16x32_bf16 v[86:89], v[170:173], v[202:205], v[86:89]
	v_mfma_f32_16x16x32_bf16 v[82:85], v[178:181], v[202:205], v[82:85]
	v_mfma_f32_16x16x32_bf16 v[70:73], v[170:173], v[210:213], v[70:73]
	v_mfma_f32_16x16x32_bf16 v[66:69], v[178:181], v[210:213], v[66:69]
	v_mfma_f32_16x16x32_bf16 v[118:121], v[174:177], v[190:193], v[118:121]
	v_mfma_f32_16x16x32_bf16 v[114:117], v[182:185], v[190:193], v[114:117]
	v_mfma_f32_16x16x32_bf16 v[102:105], v[174:177], v[198:201], v[102:105]
	v_mfma_f32_16x16x32_bf16 v[98:101], v[182:185], v[198:201], v[98:101]
	v_mfma_f32_16x16x32_bf16 v[86:89], v[174:177], v[206:209], v[86:89]
	v_mfma_f32_16x16x32_bf16 v[82:85], v[182:185], v[206:209], v[82:85]
	v_mfma_f32_16x16x32_bf16 v[70:73], v[174:177], v[214:217], v[70:73]
	v_mfma_f32_16x16x32_bf16 v[66:69], v[182:185], v[214:217], v[66:69]
	s_barrier
	s_add_i32 s26, s46, s29
	v_lshl_add_u64 v[218:219], v[218:219], 0, s[10:11]
	s_mov_b32 m0, s26
	ds_read_b128 v[186:189], v154 offset:49152
	ds_read_b128 v[190:193], v154 offset:50176
	ds_read_b128 v[194:197], v154 offset:51200
	ds_read_b128 v[198:201], v154 offset:52224
	ds_read_b128 v[202:205], v154 offset:53248
	ds_read_b128 v[206:209], v154 offset:54272
	ds_read_b128 v[210:213], v154 offset:55296
	ds_read_b128 v[214:217], v154 offset:56320
	global_load_lds_dwordx4 v[218:219], off
	s_add_i32 m0, s26, 0x2000
	s_add_u32 s24, s24, 0x80080
	v_lshl_add_u64 v[218:219], v[220:221], 0, s[10:11]
	s_addc_u32 s25, s25, 0
	s_add_i32 s26, s47, s29
	global_load_lds_dwordx4 v[218:219], off
	v_lshl_add_u64 v[218:219], s[24:25], 0, v[134:135]
	s_mov_b32 m0, s26
	s_nop 0
	global_load_lds_dwordx4 v[218:219], off
	v_lshl_add_u64 v[218:219], s[24:25], 0, v[138:139]
	s_add_i32 m0, s26, 0x2000
	s_nop 0
	global_load_lds_dwordx4 v[218:219], off
	v_lshl_add_u64 v[218:219], v[222:223], 0, s[10:11]
	s_mov_b32 m0, s38
	s_nop 0
	global_load_lds_dwordx4 v[218:219], off
	v_lshl_add_u64 v[218:219], v[224:225], 0, s[10:11]
	s_mov_b32 m0, s39
	s_nop 0
	global_load_lds_dwordx4 v[218:219], off
	s_waitcnt vmcnt(8)
	s_waitcnt lgkmcnt(0)
	s_barrier
	v_mfma_f32_16x16x32_bf16 v[62:65], v[144:147], v[186:189], v[62:65]
	v_mfma_f32_16x16x32_bf16 v[58:61], v[160:163], v[186:189], v[58:61]
	v_mfma_f32_16x16x32_bf16 v[46:49], v[144:147], v[194:197], v[46:49]
	v_mfma_f32_16x16x32_bf16 v[42:45], v[160:163], v[194:197], v[42:45]
	v_mfma_f32_16x16x32_bf16 v[30:33], v[144:147], v[202:205], v[30:33]
	v_mfma_f32_16x16x32_bf16 v[26:29], v[160:163], v[202:205], v[26:29]
	v_mfma_f32_16x16x32_bf16 v[14:17], v[144:147], v[210:213], v[14:17]
	v_mfma_f32_16x16x32_bf16 v[10:13], v[160:163], v[210:213], v[10:13]
	v_mfma_f32_16x16x32_bf16 v[62:65], v[156:159], v[190:193], v[62:65]
	v_mfma_f32_16x16x32_bf16 v[58:61], v[166:169], v[190:193], v[58:61]
	v_mfma_f32_16x16x32_bf16 v[46:49], v[156:159], v[198:201], v[46:49]
	v_mfma_f32_16x16x32_bf16 v[42:45], v[166:169], v[198:201], v[42:45]
	v_mfma_f32_16x16x32_bf16 v[30:33], v[156:159], v[206:209], v[30:33]
	v_mfma_f32_16x16x32_bf16 v[26:29], v[166:169], v[206:209], v[26:29]
	v_mfma_f32_16x16x32_bf16 v[14:17], v[156:159], v[214:217], v[14:17]
	v_mfma_f32_16x16x32_bf16 v[10:13], v[166:169], v[214:217], v[10:13]
	v_mfma_f32_16x16x32_bf16 v[54:57], v[170:173], v[186:189], v[54:57]
	v_mfma_f32_16x16x32_bf16 v[50:53], v[178:181], v[186:189], v[50:53]
	v_mfma_f32_16x16x32_bf16 v[38:41], v[170:173], v[194:197], v[38:41]
	v_mfma_f32_16x16x32_bf16 v[34:37], v[178:181], v[194:197], v[34:37]
	v_mfma_f32_16x16x32_bf16 v[22:25], v[170:173], v[202:205], v[22:25]
	v_mfma_f32_16x16x32_bf16 v[18:21], v[178:181], v[202:205], v[18:21]
	v_mfma_f32_16x16x32_bf16 v[6:9], v[170:173], v[210:213], v[6:9]
	v_mfma_f32_16x16x32_bf16 v[2:5], v[178:181], v[210:213], v[2:5]
	v_mfma_f32_16x16x32_bf16 v[54:57], v[174:177], v[190:193], v[54:57]
	v_mfma_f32_16x16x32_bf16 v[50:53], v[182:185], v[190:193], v[50:53]
	v_mfma_f32_16x16x32_bf16 v[38:41], v[174:177], v[198:201], v[38:41]
	v_mfma_f32_16x16x32_bf16 v[34:37], v[182:185], v[198:201], v[34:37]
	v_mfma_f32_16x16x32_bf16 v[22:25], v[174:177], v[206:209], v[22:25]
	v_mfma_f32_16x16x32_bf16 v[18:21], v[182:185], v[206:209], v[18:21]
	v_mfma_f32_16x16x32_bf16 v[6:9], v[174:177], v[214:217], v[6:9]
	v_mfma_f32_16x16x32_bf16 v[2:5], v[182:185], v[214:217], v[2:5]
	s_barrier
	s_add_i32 s45, s45, 2
	s_add_u32 s22, s22, 0x100
	s_addc_u32 s23, s23, 0
	s_add_u32 s5, s5, 0x100
	s_addc_u32 s15, s15, 0
	s_cmp_gt_u32 s45, 29
	s_cbranch_scc0 .LBB0_704
	s_setprio 0
	s_and_b64 vcc, exec, s[12:13]
	s_cbranch_vccz .LBB0_707
	s_barrier

.Lsp_p5:
.LBB0_842:
	v_add_u32_e32 v158, s36, v152
	v_add_u32_e32 v162, s37, v152
	ds_read_b128 v[142:145], v158
	ds_read_b128 v[146:149], v158 offset:1024
	ds_read_b128 v[154:157], v158 offset:2048
	ds_read_b128 v[158:161], v158 offset:3072
	ds_read_b128 v[166:169], v162
	ds_read_b128 v[170:173], v162 offset:1024
	ds_read_b128 v[174:177], v162 offset:2048
	ds_read_b128 v[178:181], v162 offset:3072
	s_add_i32 s49, s20, 2
	s_add_u32 s21, s4, 0xfffa0080
	s_addc_u32 s22, s5, -1
	s_cmp_eq_u32 s46, s20
	s_cselect_b32 s20, s16, s47
	s_cselect_b32 s23, s15, s22
	s_cselect_b32 s22, s14, s21
	s_cselect_b32 s21, s17, s48
	v_lshl_add_u64 v[162:163], s[4:5], 0, v[138:139]
	s_add_i32 m0, s26, 0xc000
	ds_read_b128 v[182:185], v153
	ds_read_b128 v[186:189], v153 offset:1024
	ds_read_b128 v[190:193], v153 offset:2048
	ds_read_b128 v[194:197], v153 offset:3072
	ds_read_b128 v[198:201], v153 offset:4096
	ds_read_b128 v[202:205], v153 offset:5120
	ds_read_b128 v[206:209], v153 offset:6144
	ds_read_b128 v[210:213], v153 offset:7168
	global_load_lds_dwordx4 v[162:163], off
	v_lshl_add_u64 v[162:163], s[4:5], 0, v[140:141]
	s_add_i32 m0, s26, 0xe000
	s_nop 0
	global_load_lds_dwordx4 v[162:163], off
	s_waitcnt vmcnt(8)
	s_waitcnt lgkmcnt(0)
	s_barrier
	v_mfma_f32_16x16x32_bf16 v[126:129], v[142:145], v[182:185], v[126:129]
	v_mfma_f32_16x16x32_bf16 v[122:125], v[154:157], v[182:185], v[122:125]
	v_mfma_f32_16x16x32_bf16 v[118:121], v[142:145], v[190:193], v[118:121]
	v_mfma_f32_16x16x32_bf16 v[114:117], v[154:157], v[190:193], v[114:117]
	v_mfma_f32_16x16x32_bf16 v[110:113], v[142:145], v[198:201], v[110:113]
	v_mfma_f32_16x16x32_bf16 v[106:109], v[154:157], v[198:201], v[106:109]
	v_mfma_f32_16x16x32_bf16 v[102:105], v[142:145], v[206:209], v[102:105]
	v_mfma_f32_16x16x32_bf16 v[98:101], v[154:157], v[206:209], v[98:101]
	v_mfma_f32_16x16x32_bf16 v[126:129], v[146:149], v[186:189], v[126:129]
	v_mfma_f32_16x16x32_bf16 v[122:125], v[158:161], v[186:189], v[122:125]
	v_mfma_f32_16x16x32_bf16 v[118:121], v[146:149], v[194:197], v[118:121]
	v_mfma_f32_16x16x32_bf16 v[114:117], v[158:161], v[194:197], v[114:117]
	v_mfma_f32_16x16x32_bf16 v[110:113], v[146:149], v[202:205], v[110:113]
	v_mfma_f32_16x16x32_bf16 v[106:109], v[158:161], v[202:205], v[106:109]
	v_mfma_f32_16x16x32_bf16 v[102:105], v[146:149], v[210:213], v[102:105]
	v_mfma_f32_16x16x32_bf16 v[98:101], v[158:161], v[210:213], v[98:101]
	v_mfma_f32_16x16x32_bf16 v[94:97], v[166:169], v[182:185], v[94:97]
	v_mfma_f32_16x16x32_bf16 v[90:93], v[174:177], v[182:185], v[90:93]
	v_mfma_f32_16x16x32_bf16 v[86:89], v[166:169], v[190:193], v[86:89]
	v_mfma_f32_16x16x32_bf16 v[82:85], v[174:177], v[190:193], v[82:85]
	v_mfma_f32_16x16x32_bf16 v[78:81], v[166:169], v[198:201], v[78:81]
	v_mfma_f32_16x16x32_bf16 v[74:77], v[174:177], v[198:201], v[74:77]
	v_mfma_f32_16x16x32_bf16 v[70:73], v[166:169], v[206:209], v[70:73]
	v_mfma_f32_16x16x32_bf16 v[66:69], v[174:177], v[206:209], v[66:69]
	v_mfma_f32_16x16x32_bf16 v[94:97], v[170:173], v[186:189], v[94:97]
	v_mfma_f32_16x16x32_bf16 v[90:93], v[178:181], v[186:189], v[90:93]
	v_mfma_f32_16x16x32_bf16 v[86:89], v[170:173], v[194:197], v[86:89]
	v_mfma_f32_16x16x32_bf16 v[82:85], v[178:181], v[194:197], v[82:85]
	v_mfma_f32_16x16x32_bf16 v[78:81], v[170:173], v[202:205], v[78:81]
	v_mfma_f32_16x16x32_bf16 v[74:77], v[178:181], v[202:205], v[74:77]
	v_mfma_f32_16x16x32_bf16 v[70:73], v[170:173], v[210:213], v[70:73]
	v_mfma_f32_16x16x32_bf16 v[66:69], v[178:181], v[210:213], v[66:69]
	s_barrier
	s_add_i32 s50, s36, s25
	v_lshl_add_u64 v[162:163], s[20:21], 0, v[132:133]
	s_mov_b32 m0, s50
	ds_read_b128 v[182:185], v153 offset:16384
	ds_read_b128 v[186:189], v153 offset:17408
	ds_read_b128 v[190:193], v153 offset:18432
	ds_read_b128 v[194:197], v153 offset:19456
	ds_read_b128 v[198:201], v153 offset:20480
	ds_read_b128 v[202:205], v153 offset:21504
	ds_read_b128 v[206:209], v153 offset:22528
	ds_read_b128 v[210:213], v153 offset:23552
	global_load_lds_dwordx4 v[162:163], off
	s_add_i32 m0, s50, 0x2000
	s_add_u32 s50, s20, 0x60000
	v_lshl_add_u64 v[214:215], s[20:21], 0, v[136:137]
	s_addc_u32 s51, s21, 0
	s_add_i32 s52, s37, s25
	global_load_lds_dwordx4 v[214:215], off
	v_lshl_add_u64 v[216:217], s[50:51], 0, v[132:133]
	s_mov_b32 m0, s52
	v_lshl_add_u64 v[218:219], s[22:23], 0, v[134:135]
	global_load_lds_dwordx4 v[216:217], off
	v_lshl_add_u64 v[216:217], s[50:51], 0, v[136:137]
	s_add_i32 m0, s52, 0x2000
	s_nop 0
	global_load_lds_dwordx4 v[216:217], off
	v_lshl_add_u64 v[216:217], s[22:23], 0, v[130:131]
	s_mov_b32 m0, s26
	s_nop 0
	global_load_lds_dwordx4 v[216:217], off
	s_mov_b32 m0, s27
	s_nop 0
	global_load_lds_dwordx4 v[218:219], off
	s_waitcnt vmcnt(8)
	s_waitcnt lgkmcnt(0)
	s_barrier
	v_mfma_f32_16x16x32_bf16 v[62:65], v[142:145], v[182:185], v[62:65]
	v_mfma_f32_16x16x32_bf16 v[58:61], v[154:157], v[182:185], v[58:61]
	v_mfma_f32_16x16x32_bf16 v[54:57], v[142:145], v[190:193], v[54:57]
	v_mfma_f32_16x16x32_bf16 v[50:53], v[154:157], v[190:193], v[50:53]
	v_mfma_f32_16x16x32_bf16 v[46:49], v[142:145], v[198:201], v[46:49]
	v_mfma_f32_16x16x32_bf16 v[42:45], v[154:157], v[198:201], v[42:45]
	v_mfma_f32_16x16x32_bf16 v[38:41], v[142:145], v[206:209], v[38:41]
	v_mfma_f32_16x16x32_bf16 v[34:37], v[154:157], v[206:209], v[34:37]
	v_mfma_f32_16x16x32_bf16 v[62:65], v[146:149], v[186:189], v[62:65]
	v_mfma_f32_16x16x32_bf16 v[58:61], v[158:161], v[186:189], v[58:61]
	v_mfma_f32_16x16x32_bf16 v[54:57], v[146:149], v[194:197], v[54:57]
	v_mfma_f32_16x16x32_bf16 v[50:53], v[158:161], v[194:197], v[50:53]
	v_mfma_f32_16x16x32_bf16 v[46:49], v[146:149], v[202:205], v[46:49]
	v_mfma_f32_16x16x32_bf16 v[42:45], v[158:161], v[202:205], v[42:45]
	v_mfma_f32_16x16x32_bf16 v[38:41], v[146:149], v[210:213], v[38:41]
	v_mfma_f32_16x16x32_bf16 v[34:37], v[158:161], v[210:213], v[34:37]
	v_mfma_f32_16x16x32_bf16 v[30:33], v[166:169], v[182:185], v[30:33]
	v_mfma_f32_16x16x32_bf16 v[26:29], v[174:177], v[182:185], v[26:29]
	v_mfma_f32_16x16x32_bf16 v[22:25], v[166:169], v[190:193], v[22:25]
	v_mfma_f32_16x16x32_bf16 v[18:21], v[174:177], v[190:193], v[18:21]
	v_mfma_f32_16x16x32_bf16 v[14:17], v[166:169], v[198:201], v[14:17]
	v_mfma_f32_16x16x32_bf16 v[10:13], v[174:177], v[198:201], v[10:13]
	v_mfma_f32_16x16x32_bf16 v[6:9], v[166:169], v[206:209], v[6:9]
	v_mfma_f32_16x16x32_bf16 v[2:5], v[174:177], v[206:209], v[2:5]
	v_mfma_f32_16x16x32_bf16 v[30:33], v[170:173], v[186:189], v[30:33]
	v_mfma_f32_16x16x32_bf16 v[26:29], v[178:181], v[186:189], v[26:29]
	v_mfma_f32_16x16x32_bf16 v[22:25], v[170:173], v[194:197], v[22:25]
	v_mfma_f32_16x16x32_bf16 v[18:21], v[178:181], v[194:197], v[18:21]
	v_mfma_f32_16x16x32_bf16 v[14:17], v[170:173], v[202:205], v[14:17]
	v_mfma_f32_16x16x32_bf16 v[10:13], v[178:181], v[202:205], v[10:13]
	v_mfma_f32_16x16x32_bf16 v[6:9], v[170:173], v[210:213], v[6:9]
	v_mfma_f32_16x16x32_bf16 v[2:5], v[178:181], v[210:213], v[2:5]
	s_barrier
	s_add_i32 s50, 0, 0x18000
	s_add_i32 s51, 0, 0x1c000
	v_add_u32_e32 v158, s50, v152
	v_add_u32_e32 v164, s51, v152
	ds_read_b128 v[142:145], v158
	ds_read_b128 v[146:149], v158 offset:1024
	ds_read_b128 v[154:157], v158 offset:2048
	ds_read_b128 v[158:161], v158 offset:3072
	ds_read_b128 v[166:169], v164
	ds_read_b128 v[170:173], v164 offset:1024
	ds_read_b128 v[174:177], v164 offset:2048
	ds_read_b128 v[178:181], v164 offset:3072
	s_add_u32 s22, s22, 0x60000
	s_addc_u32 s23, s23, 0
	s_mov_b32 m0, s28
	v_lshl_add_u64 v[220:221], s[22:23], 0, v[130:131]
	ds_read_b128 v[182:185], v153 offset:32768
	ds_read_b128 v[186:189], v153 offset:33792
	ds_read_b128 v[190:193], v153 offset:34816
	ds_read_b128 v[194:197], v153 offset:35840
	ds_read_b128 v[198:201], v153 offset:36864
	ds_read_b128 v[202:205], v153 offset:37888
	ds_read_b128 v[206:209], v153 offset:38912
	ds_read_b128 v[210:213], v153 offset:39936
	global_load_lds_dwordx4 v[220:221], off
	v_lshl_add_u64 v[220:221], s[22:23], 0, v[134:135]
	s_mov_b32 m0, s29
	s_nop 0
	global_load_lds_dwordx4 v[220:221], off
	s_waitcnt vmcnt(8)
	s_waitcnt lgkmcnt(0)
	s_barrier
	v_mfma_f32_16x16x32_bf16 v[126:129], v[142:145], v[182:185], v[126:129]
	v_mfma_f32_16x16x32_bf16 v[122:125], v[154:157], v[182:185], v[122:125]
	v_mfma_f32_16x16x32_bf16 v[118:121], v[142:145], v[190:193], v[118:121]
	v_mfma_f32_16x16x32_bf16 v[114:117], v[154:157], v[190:193], v[114:117]
	v_mfma_f32_16x16x32_bf16 v[110:113], v[142:145], v[198:201], v[110:113]
	v_mfma_f32_16x16x32_bf16 v[106:109], v[154:157], v[198:201], v[106:109]
	v_mfma_f32_16x16x32_bf16 v[102:105], v[142:145], v[206:209], v[102:105]
	v_mfma_f32_16x16x32_bf16 v[98:101], v[154:157], v[206:209], v[98:101]
	v_mfma_f32_16x16x32_bf16 v[126:129], v[146:149], v[186:189], v[126:129]
	v_mfma_f32_16x16x32_bf16 v[122:125], v[158:161], v[186:189], v[122:125]
	v_mfma_f32_16x16x32_bf16 v[118:121], v[146:149], v[194:197], v[118:121]
	v_mfma_f32_16x16x32_bf16 v[114:117], v[158:161], v[194:197], v[114:117]
	v_mfma_f32_16x16x32_bf16 v[110:113], v[146:149], v[202:205], v[110:113]
	v_mfma_f32_16x16x32_bf16 v[106:109], v[158:161], v[202:205], v[106:109]
	v_mfma_f32_16x16x32_bf16 v[102:105], v[146:149], v[210:213], v[102:105]
	v_mfma_f32_16x16x32_bf16 v[98:101], v[158:161], v[210:213], v[98:101]
	v_mfma_f32_16x16x32_bf16 v[94:97], v[166:169], v[182:185], v[94:97]
	v_mfma_f32_16x16x32_bf16 v[90:93], v[174:177], v[182:185], v[90:93]
	v_mfma_f32_16x16x32_bf16 v[86:89], v[166:169], v[190:193], v[86:89]
	v_mfma_f32_16x16x32_bf16 v[82:85], v[174:177], v[190:193], v[82:85]
	v_mfma_f32_16x16x32_bf16 v[78:81], v[166:169], v[198:201], v[78:81]
	v_mfma_f32_16x16x32_bf16 v[74:77], v[174:177], v[198:201], v[74:77]
	v_mfma_f32_16x16x32_bf16 v[70:73], v[166:169], v[206:209], v[70:73]
	v_mfma_f32_16x16x32_bf16 v[66:69], v[174:177], v[206:209], v[66:69]
	v_mfma_f32_16x16x32_bf16 v[94:97], v[170:173], v[186:189], v[94:97]
	v_mfma_f32_16x16x32_bf16 v[90:93], v[178:181], v[186:189], v[90:93]
	v_mfma_f32_16x16x32_bf16 v[86:89], v[170:173], v[194:197], v[86:89]
	v_mfma_f32_16x16x32_bf16 v[82:85], v[178:181], v[194:197], v[82:85]
	v_mfma_f32_16x16x32_bf16 v[78:81], v[170:173], v[202:205], v[78:81]
	v_mfma_f32_16x16x32_bf16 v[74:77], v[178:181], v[202:205], v[74:77]
	v_mfma_f32_16x16x32_bf16 v[70:73], v[170:173], v[210:213], v[70:73]
	v_mfma_f32_16x16x32_bf16 v[66:69], v[178:181], v[210:213], v[66:69]
	s_barrier
	s_add_i32 s22, s50, s25
	v_lshl_add_u64 v[162:163], v[162:163], 0, s[8:9]
	s_mov_b32 m0, s22
	ds_read_b128 v[182:185], v153 offset:49152
	ds_read_b128 v[186:189], v153 offset:50176
	ds_read_b128 v[190:193], v153 offset:51200
	ds_read_b128 v[194:197], v153 offset:52224
	ds_read_b128 v[198:201], v153 offset:53248
	ds_read_b128 v[202:205], v153 offset:54272
	ds_read_b128 v[206:209], v153 offset:55296
	ds_read_b128 v[210:213], v153 offset:56320
	global_load_lds_dwordx4 v[162:163], off
	s_add_i32 m0, s22, 0x2000
	s_add_u32 s20, s20, 0x60080
	v_lshl_add_u64 v[162:163], v[214:215], 0, s[8:9]
	s_addc_u32 s21, s21, 0
	s_add_i32 s22, s51, s25
	global_load_lds_dwordx4 v[162:163], off
	v_lshl_add_u64 v[162:163], s[20:21], 0, v[132:133]
	s_mov_b32 m0, s22
	s_nop 0
	global_load_lds_dwordx4 v[162:163], off
	v_lshl_add_u64 v[162:163], s[20:21], 0, v[136:137]
	s_add_i32 m0, s22, 0x2000
	s_nop 0
	global_load_lds_dwordx4 v[162:163], off
	v_lshl_add_u64 v[162:163], v[216:217], 0, s[8:9]
	s_mov_b32 m0, s34
	s_nop 0
	global_load_lds_dwordx4 v[162:163], off
	v_lshl_add_u64 v[162:163], v[218:219], 0, s[8:9]
	s_mov_b32 m0, s35
	s_nop 0
	global_load_lds_dwordx4 v[162:163], off
	s_waitcnt vmcnt(8)
	s_waitcnt lgkmcnt(0)
	s_barrier
	v_mfma_f32_16x16x32_bf16 v[62:65], v[142:145], v[182:185], v[62:65]
	v_mfma_f32_16x16x32_bf16 v[58:61], v[154:157], v[182:185], v[58:61]
	v_mfma_f32_16x16x32_bf16 v[54:57], v[142:145], v[190:193], v[54:57]
	v_mfma_f32_16x16x32_bf16 v[50:53], v[154:157], v[190:193], v[50:53]
	v_mfma_f32_16x16x32_bf16 v[46:49], v[142:145], v[198:201], v[46:49]
	v_mfma_f32_16x16x32_bf16 v[42:45], v[154:157], v[198:201], v[42:45]
	v_mfma_f32_16x16x32_bf16 v[38:41], v[142:145], v[206:209], v[38:41]
	v_mfma_f32_16x16x32_bf16 v[34:37], v[154:157], v[206:209], v[34:37]
	v_mfma_f32_16x16x32_bf16 v[62:65], v[146:149], v[186:189], v[62:65]
	v_mfma_f32_16x16x32_bf16 v[58:61], v[158:161], v[186:189], v[58:61]
	v_mfma_f32_16x16x32_bf16 v[54:57], v[146:149], v[194:197], v[54:57]
	v_mfma_f32_16x16x32_bf16 v[50:53], v[158:161], v[194:197], v[50:53]
	v_mfma_f32_16x16x32_bf16 v[46:49], v[146:149], v[202:205], v[46:49]
	v_mfma_f32_16x16x32_bf16 v[42:45], v[158:161], v[202:205], v[42:45]
	v_mfma_f32_16x16x32_bf16 v[38:41], v[146:149], v[210:213], v[38:41]
	v_mfma_f32_16x16x32_bf16 v[34:37], v[158:161], v[210:213], v[34:37]
	v_mfma_f32_16x16x32_bf16 v[30:33], v[166:169], v[182:185], v[30:33]
	v_mfma_f32_16x16x32_bf16 v[26:29], v[174:177], v[182:185], v[26:29]
	v_mfma_f32_16x16x32_bf16 v[22:25], v[166:169], v[190:193], v[22:25]
	v_mfma_f32_16x16x32_bf16 v[18:21], v[174:177], v[190:193], v[18:21]
	v_mfma_f32_16x16x32_bf16 v[14:17], v[166:169], v[198:201], v[14:17]
	v_mfma_f32_16x16x32_bf16 v[10:13], v[174:177], v[198:201], v[10:13]
	v_mfma_f32_16x16x32_bf16 v[6:9], v[166:169], v[206:209], v[6:9]
	v_mfma_f32_16x16x32_bf16 v[2:5], v[174:177], v[206:209], v[2:5]
	v_mfma_f32_16x16x32_bf16 v[30:33], v[170:173], v[186:189], v[30:33]
	v_mfma_f32_16x16x32_bf16 v[26:29], v[178:181], v[186:189], v[26:29]
	v_mfma_f32_16x16x32_bf16 v[22:25], v[170:173], v[194:197], v[22:25]
	v_mfma_f32_16x16x32_bf16 v[18:21], v[178:181], v[194:197], v[18:21]
	v_mfma_f32_16x16x32_bf16 v[14:17], v[170:173], v[202:205], v[14:17]
	v_mfma_f32_16x16x32_bf16 v[10:13], v[178:181], v[202:205], v[10:13]
	v_mfma_f32_16x16x32_bf16 v[6:9], v[170:173], v[210:213], v[6:9]
	v_mfma_f32_16x16x32_bf16 v[2:5], v[178:181], v[210:213], v[2:5]
	s_barrier
	s_add_u32 s4, s4, 0x100
	s_addc_u32 s5, s5, 0
	s_add_u32 s47, s47, 0x100
	s_addc_u32 s48, s48, 0
	s_cmp_ge_i32 s49, s45
	s_mov_b32 s20, s49
	s_cbranch_scc0 .LBB0_842
	s_setprio 0
	s_and_b64 vcc, exec, s[10:11]
	s_cbranch_vccz .LBB0_845
	s_barrier

.Lsp_p6:
.LBB0_1019:
	ds_read_b128 v[142:145], v149
	ds_read_b128 v[154:157], v149 offset:1024
	ds_read_b128 v[158:161], v149 offset:2048
	ds_read_b128 v[166:169], v149 offset:3072
	ds_read_b128 v[170:173], v150
	ds_read_b128 v[174:177], v150 offset:1024
	ds_read_b128 v[178:181], v150 offset:2048
	ds_read_b128 v[182:185], v150 offset:3072
	s_add_u32 s28, s26, 0xfff80080
	s_addc_u32 s29, s27, -1
	s_cmp_eq_u32 s49, 28
	s_cselect_b32 s31, s1, s29
	s_cselect_b32 s30, s15, s28
	s_cselect_b32 s29, s17, s48
	s_cselect_b32 s28, s46, s47
	v_lshl_add_u64 v[162:163], s[26:27], 0, v[138:139]
	s_add_i32 m0, s34, 0xc000
	ds_read_b128 v[186:189], v151
	ds_read_b128 v[190:193], v151 offset:1024
	ds_read_b128 v[194:197], v151 offset:2048
	ds_read_b128 v[198:201], v151 offset:3072
	ds_read_b128 v[202:205], v151 offset:4096
	ds_read_b128 v[206:209], v151 offset:5120
	ds_read_b128 v[210:213], v151 offset:6144
	ds_read_b128 v[214:217], v151 offset:7168
	global_load_lds_dwordx4 v[162:163], off
	v_lshl_add_u64 v[162:163], s[26:27], 0, v[140:141]
	s_add_i32 m0, s34, 0xe000
	s_nop 0
	global_load_lds_dwordx4 v[162:163], off
	s_waitcnt vmcnt(8)
	s_waitcnt lgkmcnt(0)
	s_barrier
	v_mfma_f32_16x16x32_bf16 v[126:129], v[142:145], v[186:189], v[126:129]
	v_mfma_f32_16x16x32_bf16 v[122:125], v[158:161], v[186:189], v[122:125]
	v_mfma_f32_16x16x32_bf16 v[110:113], v[142:145], v[194:197], v[110:113]
	v_mfma_f32_16x16x32_bf16 v[106:109], v[158:161], v[194:197], v[106:109]
	v_mfma_f32_16x16x32_bf16 v[94:97], v[142:145], v[202:205], v[94:97]
	v_mfma_f32_16x16x32_bf16 v[90:93], v[158:161], v[202:205], v[90:93]
	v_mfma_f32_16x16x32_bf16 v[78:81], v[142:145], v[210:213], v[78:81]
	v_mfma_f32_16x16x32_bf16 v[74:77], v[158:161], v[210:213], v[74:77]
	v_mfma_f32_16x16x32_bf16 v[126:129], v[154:157], v[190:193], v[126:129]
	v_mfma_f32_16x16x32_bf16 v[122:125], v[166:169], v[190:193], v[122:125]
	v_mfma_f32_16x16x32_bf16 v[110:113], v[154:157], v[198:201], v[110:113]
	v_mfma_f32_16x16x32_bf16 v[106:109], v[166:169], v[198:201], v[106:109]
	v_mfma_f32_16x16x32_bf16 v[94:97], v[154:157], v[206:209], v[94:97]
	v_mfma_f32_16x16x32_bf16 v[90:93], v[166:169], v[206:209], v[90:93]
	v_mfma_f32_16x16x32_bf16 v[78:81], v[154:157], v[214:217], v[78:81]
	v_mfma_f32_16x16x32_bf16 v[74:77], v[166:169], v[214:217], v[74:77]
	v_mfma_f32_16x16x32_bf16 v[118:121], v[170:173], v[186:189], v[118:121]
	v_mfma_f32_16x16x32_bf16 v[114:117], v[178:181], v[186:189], v[114:117]
	v_mfma_f32_16x16x32_bf16 v[102:105], v[170:173], v[194:197], v[102:105]
	v_mfma_f32_16x16x32_bf16 v[98:101], v[178:181], v[194:197], v[98:101]
	v_mfma_f32_16x16x32_bf16 v[86:89], v[170:173], v[202:205], v[86:89]
	v_mfma_f32_16x16x32_bf16 v[82:85], v[178:181], v[202:205], v[82:85]
	v_mfma_f32_16x16x32_bf16 v[70:73], v[170:173], v[210:213], v[70:73]
	v_mfma_f32_16x16x32_bf16 v[66:69], v[178:181], v[210:213], v[66:69]
	v_mfma_f32_16x16x32_bf16 v[118:121], v[174:177], v[190:193], v[118:121]
	v_mfma_f32_16x16x32_bf16 v[114:117], v[182:185], v[190:193], v[114:117]
	v_mfma_f32_16x16x32_bf16 v[102:105], v[174:177], v[198:201], v[102:105]
	v_mfma_f32_16x16x32_bf16 v[98:101], v[182:185], v[198:201], v[98:101]
	v_mfma_f32_16x16x32_bf16 v[86:89], v[174:177], v[206:209], v[86:89]
	v_mfma_f32_16x16x32_bf16 v[82:85], v[182:185], v[206:209], v[82:85]
	v_mfma_f32_16x16x32_bf16 v[70:73], v[174:177], v[214:217], v[70:73]
	v_mfma_f32_16x16x32_bf16 v[66:69], v[182:185], v[214:217], v[66:69]
	s_barrier
	s_add_i32 s50, s44, s25
	v_lshl_add_u64 v[162:163], s[28:29], 0, v[132:133]
	s_mov_b32 m0, s50
	ds_read_b128 v[186:189], v151 offset:16384
	ds_read_b128 v[190:193], v151 offset:17408
	ds_read_b128 v[194:197], v151 offset:18432
	ds_read_b128 v[198:201], v151 offset:19456
	ds_read_b128 v[202:205], v151 offset:20480
	ds_read_b128 v[206:209], v151 offset:21504
	ds_read_b128 v[210:213], v151 offset:22528
	ds_read_b128 v[214:217], v151 offset:23552
	global_load_lds_dwordx4 v[162:163], off
	s_add_i32 m0, s50, 0x2000
	s_add_u32 s50, s28, 0x80000
	v_lshl_add_u64 v[218:219], s[28:29], 0, v[136:137]
	s_addc_u32 s51, s29, 0
	s_add_i32 s52, s45, s25
	global_load_lds_dwordx4 v[218:219], off
	v_lshl_add_u64 v[220:221], s[50:51], 0, v[132:133]
	s_mov_b32 m0, s52
	v_lshl_add_u64 v[222:223], s[30:31], 0, v[134:135]
	global_load_lds_dwordx4 v[220:221], off
	v_lshl_add_u64 v[220:221], s[50:51], 0, v[136:137]
	s_add_i32 m0, s52, 0x2000
	s_nop 0
	global_load_lds_dwordx4 v[220:221], off
	v_lshl_add_u64 v[220:221], s[30:31], 0, v[130:131]
	s_mov_b32 m0, s34
	s_nop 0
	global_load_lds_dwordx4 v[220:221], off
	s_mov_b32 m0, s35
	s_nop 0
	global_load_lds_dwordx4 v[222:223], off
	s_waitcnt vmcnt(8)
	s_waitcnt lgkmcnt(0)
	s_barrier
	v_mfma_f32_16x16x32_bf16 v[62:65], v[142:145], v[186:189], v[62:65]
	v_mfma_f32_16x16x32_bf16 v[58:61], v[158:161], v[186:189], v[58:61]
	v_mfma_f32_16x16x32_bf16 v[46:49], v[142:145], v[194:197], v[46:49]
	v_mfma_f32_16x16x32_bf16 v[42:45], v[158:161], v[194:197], v[42:45]
	v_mfma_f32_16x16x32_bf16 v[30:33], v[142:145], v[202:205], v[30:33]
	v_mfma_f32_16x16x32_bf16 v[26:29], v[158:161], v[202:205], v[26:29]
	v_mfma_f32_16x16x32_bf16 v[14:17], v[142:145], v[210:213], v[14:17]
	v_mfma_f32_16x16x32_bf16 v[10:13], v[158:161], v[210:213], v[10:13]
	v_mfma_f32_16x16x32_bf16 v[62:65], v[154:157], v[190:193], v[62:65]
	v_mfma_f32_16x16x32_bf16 v[58:61], v[166:169], v[190:193], v[58:61]
	v_mfma_f32_16x16x32_bf16 v[46:49], v[154:157], v[198:201], v[46:49]
	v_mfma_f32_16x16x32_bf16 v[42:45], v[166:169], v[198:201], v[42:45]
	v_mfma_f32_16x16x32_bf16 v[30:33], v[154:157], v[206:209], v[30:33]
	v_mfma_f32_16x16x32_bf16 v[26:29], v[166:169], v[206:209], v[26:29]
	v_mfma_f32_16x16x32_bf16 v[14:17], v[154:157], v[214:217], v[14:17]
	v_mfma_f32_16x16x32_bf16 v[10:13], v[166:169], v[214:217], v[10:13]
	v_mfma_f32_16x16x32_bf16 v[54:57], v[170:173], v[186:189], v[54:57]
	v_mfma_f32_16x16x32_bf16 v[50:53], v[178:181], v[186:189], v[50:53]
	v_mfma_f32_16x16x32_bf16 v[38:41], v[170:173], v[194:197], v[38:41]
	v_mfma_f32_16x16x32_bf16 v[34:37], v[178:181], v[194:197], v[34:37]
	v_mfma_f32_16x16x32_bf16 v[22:25], v[170:173], v[202:205], v[22:25]
	v_mfma_f32_16x16x32_bf16 v[18:21], v[178:181], v[202:205], v[18:21]
	v_mfma_f32_16x16x32_bf16 v[6:9], v[170:173], v[210:213], v[6:9]
	v_mfma_f32_16x16x32_bf16 v[2:5], v[178:181], v[210:213], v[2:5]
	v_mfma_f32_16x16x32_bf16 v[54:57], v[174:177], v[190:193], v[54:57]
	v_mfma_f32_16x16x32_bf16 v[50:53], v[182:185], v[190:193], v[50:53]
	v_mfma_f32_16x16x32_bf16 v[38:41], v[174:177], v[198:201], v[38:41]
	v_mfma_f32_16x16x32_bf16 v[34:37], v[182:185], v[198:201], v[34:37]
	v_mfma_f32_16x16x32_bf16 v[22:25], v[174:177], v[206:209], v[22:25]
	v_mfma_f32_16x16x32_bf16 v[18:21], v[182:185], v[206:209], v[18:21]
	v_mfma_f32_16x16x32_bf16 v[6:9], v[174:177], v[214:217], v[6:9]
	v_mfma_f32_16x16x32_bf16 v[2:5], v[182:185], v[214:217], v[2:5]
	s_barrier
	s_add_i32 s50, 0, 0x18000
	v_add_u32_e32 v153, s50, v148
	s_add_i32 s51, 0, 0x1c000
	ds_read_b128 v[142:145], v153
	ds_read_b128 v[154:157], v153 offset:1024
	ds_read_b128 v[158:161], v153 offset:2048
	ds_read_b128 v[166:169], v153 offset:3072
	v_add_u32_e32 v153, s51, v148
	ds_read_b128 v[170:173], v153
	ds_read_b128 v[174:177], v153 offset:1024
	ds_read_b128 v[178:181], v153 offset:2048
	ds_read_b128 v[182:185], v153 offset:3072
	s_add_u32 s30, s30, 0x80000
	s_addc_u32 s31, s31, 0
	s_mov_b32 m0, s36
	v_lshl_add_u64 v[224:225], s[30:31], 0, v[130:131]
	ds_read_b128 v[186:189], v151 offset:32768
	ds_read_b128 v[190:193], v151 offset:33792
	ds_read_b128 v[194:197], v151 offset:34816
	ds_read_b128 v[198:201], v151 offset:35840
	ds_read_b128 v[202:205], v151 offset:36864
	ds_read_b128 v[206:209], v151 offset:37888
	ds_read_b128 v[210:213], v151 offset:38912
	ds_read_b128 v[214:217], v151 offset:39936
	global_load_lds_dwordx4 v[224:225], off
	v_lshl_add_u64 v[224:225], s[30:31], 0, v[134:135]
	s_mov_b32 m0, s37
	s_nop 0
	global_load_lds_dwordx4 v[224:225], off
	s_waitcnt vmcnt(8)
	s_waitcnt lgkmcnt(0)
	s_barrier
	v_mfma_f32_16x16x32_bf16 v[126:129], v[142:145], v[186:189], v[126:129]
	v_mfma_f32_16x16x32_bf16 v[122:125], v[158:161], v[186:189], v[122:125]
	v_mfma_f32_16x16x32_bf16 v[110:113], v[142:145], v[194:197], v[110:113]
	v_mfma_f32_16x16x32_bf16 v[106:109], v[158:161], v[194:197], v[106:109]
	v_mfma_f32_16x16x32_bf16 v[94:97], v[142:145], v[202:205], v[94:97]
	v_mfma_f32_16x16x32_bf16 v[90:93], v[158:161], v[202:205], v[90:93]
	v_mfma_f32_16x16x32_bf16 v[78:81], v[142:145], v[210:213], v[78:81]
	v_mfma_f32_16x16x32_bf16 v[74:77], v[158:161], v[210:213], v[74:77]
	v_mfma_f32_16x16x32_bf16 v[126:129], v[154:157], v[190:193], v[126:129]
	v_mfma_f32_16x16x32_bf16 v[122:125], v[166:169], v[190:193], v[122:125]
	v_mfma_f32_16x16x32_bf16 v[110:113], v[154:157], v[198:201], v[110:113]
	v_mfma_f32_16x16x32_bf16 v[106:109], v[166:169], v[198:201], v[106:109]
	v_mfma_f32_16x16x32_bf16 v[94:97], v[154:157], v[206:209], v[94:97]
	v_mfma_f32_16x16x32_bf16 v[90:93], v[166:169], v[206:209], v[90:93]
	v_mfma_f32_16x16x32_bf16 v[78:81], v[154:157], v[214:217], v[78:81]
	v_mfma_f32_16x16x32_bf16 v[74:77], v[166:169], v[214:217], v[74:77]
	v_mfma_f32_16x16x32_bf16 v[118:121], v[170:173], v[186:189], v[118:121]
	v_mfma_f32_16x16x32_bf16 v[114:117], v[178:181], v[186:189], v[114:117]
	v_mfma_f32_16x16x32_bf16 v[102:105], v[170:173], v[194:197], v[102:105]
	v_mfma_f32_16x16x32_bf16 v[98:101], v[178:181], v[194:197], v[98:101]
	v_mfma_f32_16x16x32_bf16 v[86:89], v[170:173], v[202:205], v[86:89]
	v_mfma_f32_16x16x32_bf16 v[82:85], v[178:181], v[202:205], v[82:85]
	v_mfma_f32_16x16x32_bf16 v[70:73], v[170:173], v[210:213], v[70:73]
	v_mfma_f32_16x16x32_bf16 v[66:69], v[178:181], v[210:213], v[66:69]
	v_mfma_f32_16x16x32_bf16 v[118:121], v[174:177], v[190:193], v[118:121]
	v_mfma_f32_16x16x32_bf16 v[114:117], v[182:185], v[190:193], v[114:117]
	v_mfma_f32_16x16x32_bf16 v[102:105], v[174:177], v[198:201], v[102:105]
	v_mfma_f32_16x16x32_bf16 v[98:101], v[182:185], v[198:201], v[98:101]
	v_mfma_f32_16x16x32_bf16 v[86:89], v[174:177], v[206:209], v[86:89]
	v_mfma_f32_16x16x32_bf16 v[82:85], v[182:185], v[206:209], v[82:85]
	v_mfma_f32_16x16x32_bf16 v[70:73], v[174:177], v[214:217], v[70:73]
	v_mfma_f32_16x16x32_bf16 v[66:69], v[182:185], v[214:217], v[66:69]
	s_barrier
	s_add_i32 s30, s50, s25
	v_lshl_add_u64 v[162:163], v[162:163], 0, s[8:9]
	s_mov_b32 m0, s30
	ds_read_b128 v[186:189], v151 offset:49152
	ds_read_b128 v[190:193], v151 offset:50176
	ds_read_b128 v[194:197], v151 offset:51200
	ds_read_b128 v[198:201], v151 offset:52224
	ds_read_b128 v[202:205], v151 offset:53248
	ds_read_b128 v[206:209], v151 offset:54272
	ds_read_b128 v[210:213], v151 offset:55296
	ds_read_b128 v[214:217], v151 offset:56320
	global_load_lds_dwordx4 v[162:163], off
	s_add_i32 m0, s30, 0x2000
	s_add_u32 s28, s28, 0x80080
	v_lshl_add_u64 v[162:163], v[218:219], 0, s[8:9]
	s_addc_u32 s29, s29, 0
	s_add_i32 s30, s51, s25
	global_load_lds_dwordx4 v[162:163], off
	v_lshl_add_u64 v[162:163], s[28:29], 0, v[132:133]
	s_mov_b32 m0, s30
	s_nop 0
	global_load_lds_dwordx4 v[162:163], off
	v_lshl_add_u64 v[162:163], s[28:29], 0, v[136:137]
	s_add_i32 m0, s30, 0x2000
	s_nop 0
	global_load_lds_dwordx4 v[162:163], off
	v_lshl_add_u64 v[162:163], v[220:221], 0, s[8:9]
	s_mov_b32 m0, s41
	s_nop 0
	global_load_lds_dwordx4 v[162:163], off
	v_lshl_add_u64 v[162:163], v[222:223], 0, s[8:9]
	s_mov_b32 m0, s42
	s_nop 0
	global_load_lds_dwordx4 v[162:163], off
	s_waitcnt vmcnt(8)
	s_waitcnt lgkmcnt(0)
	s_barrier
	v_mfma_f32_16x16x32_bf16 v[62:65], v[142:145], v[186:189], v[62:65]
	v_mfma_f32_16x16x32_bf16 v[58:61], v[158:161], v[186:189], v[58:61]
	v_mfma_f32_16x16x32_bf16 v[46:49], v[142:145], v[194:197], v[46:49]
	v_mfma_f32_16x16x32_bf16 v[42:45], v[158:161], v[194:197], v[42:45]
	v_mfma_f32_16x16x32_bf16 v[30:33], v[142:145], v[202:205], v[30:33]
	v_mfma_f32_16x16x32_bf16 v[26:29], v[158:161], v[202:205], v[26:29]
	v_mfma_f32_16x16x32_bf16 v[14:17], v[142:145], v[210:213], v[14:17]
	v_mfma_f32_16x16x32_bf16 v[10:13], v[158:161], v[210:213], v[10:13]
	v_mfma_f32_16x16x32_bf16 v[62:65], v[154:157], v[190:193], v[62:65]
	v_mfma_f32_16x16x32_bf16 v[58:61], v[166:169], v[190:193], v[58:61]
	v_mfma_f32_16x16x32_bf16 v[46:49], v[154:157], v[198:201], v[46:49]
	v_mfma_f32_16x16x32_bf16 v[42:45], v[166:169], v[198:201], v[42:45]
	v_mfma_f32_16x16x32_bf16 v[30:33], v[154:157], v[206:209], v[30:33]
	v_mfma_f32_16x16x32_bf16 v[26:29], v[166:169], v[206:209], v[26:29]
	v_mfma_f32_16x16x32_bf16 v[14:17], v[154:157], v[214:217], v[14:17]
	v_mfma_f32_16x16x32_bf16 v[10:13], v[166:169], v[214:217], v[10:13]
	v_mfma_f32_16x16x32_bf16 v[54:57], v[170:173], v[186:189], v[54:57]
	v_mfma_f32_16x16x32_bf16 v[50:53], v[178:181], v[186:189], v[50:53]
	v_mfma_f32_16x16x32_bf16 v[38:41], v[170:173], v[194:197], v[38:41]
	v_mfma_f32_16x16x32_bf16 v[34:37], v[178:181], v[194:197], v[34:37]
	v_mfma_f32_16x16x32_bf16 v[22:25], v[170:173], v[202:205], v[22:25]
	v_mfma_f32_16x16x32_bf16 v[18:21], v[178:181], v[202:205], v[18:21]
	v_mfma_f32_16x16x32_bf16 v[6:9], v[170:173], v[210:213], v[6:9]
	v_mfma_f32_16x16x32_bf16 v[2:5], v[178:181], v[210:213], v[2:5]
	v_mfma_f32_16x16x32_bf16 v[54:57], v[174:177], v[190:193], v[54:57]
	v_mfma_f32_16x16x32_bf16 v[50:53], v[182:185], v[190:193], v[50:53]
	v_mfma_f32_16x16x32_bf16 v[38:41], v[174:177], v[198:201], v[38:41]
	v_mfma_f32_16x16x32_bf16 v[34:37], v[182:185], v[198:201], v[34:37]
	v_mfma_f32_16x16x32_bf16 v[22:25], v[174:177], v[206:209], v[22:25]
	v_mfma_f32_16x16x32_bf16 v[18:21], v[182:185], v[206:209], v[18:21]
	v_mfma_f32_16x16x32_bf16 v[6:9], v[174:177], v[214:217], v[6:9]
	v_mfma_f32_16x16x32_bf16 v[2:5], v[182:185], v[214:217], v[2:5]
	s_barrier
	s_add_i32 s49, s49, 2
	s_add_u32 s26, s26, 0x100
	s_addc_u32 s27, s27, 0
	s_add_u32 s47, s47, 0x100
	s_addc_u32 s48, s48, 0
	s_cmp_gt_u32 s49, 29
	s_cbranch_scc0 .LBB0_1019
	s_setprio 0
	s_and_b64 vcc, exec, s[10:11]
	s_cbranch_vccz .LBB0_1022
	s_barrier

.Lsp_p9:
.LBB0_1220:
	ds_read_b128 v[142:145], v149
	ds_read_b128 v[154:157], v149 offset:1024
	ds_read_b128 v[158:161], v149 offset:2048
	ds_read_b128 v[166:169], v149 offset:3072
	ds_read_b128 v[170:173], v150
	ds_read_b128 v[174:177], v150 offset:1024
	ds_read_b128 v[178:181], v150 offset:2048
	ds_read_b128 v[182:185], v150 offset:3072
	s_add_u32 s30, s28, 0xfffe0080
	s_addc_u32 s31, s29, -1
	s_cmp_eq_u32 s51, 4
	s_cselect_b32 s35, s1, s31
	s_cselect_b32 s34, s17, s30
	s_cselect_b32 s31, s19, s50
	s_cselect_b32 s30, s48, s49
	v_lshl_add_u64 v[162:163], s[28:29], 0, v[138:139]
	s_add_i32 m0, s27, 0xc000
	ds_read_b128 v[186:189], v151
	ds_read_b128 v[190:193], v151 offset:1024
	ds_read_b128 v[194:197], v151 offset:2048
	ds_read_b128 v[198:201], v151 offset:3072
	ds_read_b128 v[202:205], v151 offset:4096
	ds_read_b128 v[206:209], v151 offset:5120
	ds_read_b128 v[210:213], v151 offset:6144
	ds_read_b128 v[214:217], v151 offset:7168
	global_load_lds_dwordx4 v[162:163], off
	v_lshl_add_u64 v[162:163], s[28:29], 0, v[140:141]
	s_add_i32 m0, s27, 0xe000
	s_nop 0
	global_load_lds_dwordx4 v[162:163], off
	s_waitcnt vmcnt(8)
	s_waitcnt lgkmcnt(0)
	s_barrier
	v_mfma_f32_16x16x32_bf16 v[126:129], v[142:145], v[186:189], v[126:129]
	v_mfma_f32_16x16x32_bf16 v[122:125], v[158:161], v[186:189], v[122:125]
	v_mfma_f32_16x16x32_bf16 v[110:113], v[142:145], v[194:197], v[110:113]
	v_mfma_f32_16x16x32_bf16 v[106:109], v[158:161], v[194:197], v[106:109]
	v_mfma_f32_16x16x32_bf16 v[94:97], v[142:145], v[202:205], v[94:97]
	v_mfma_f32_16x16x32_bf16 v[90:93], v[158:161], v[202:205], v[90:93]
	v_mfma_f32_16x16x32_bf16 v[78:81], v[142:145], v[210:213], v[78:81]
	v_mfma_f32_16x16x32_bf16 v[74:77], v[158:161], v[210:213], v[74:77]
	v_mfma_f32_16x16x32_bf16 v[126:129], v[154:157], v[190:193], v[126:129]
	v_mfma_f32_16x16x32_bf16 v[122:125], v[166:169], v[190:193], v[122:125]
	v_mfma_f32_16x16x32_bf16 v[110:113], v[154:157], v[198:201], v[110:113]
	v_mfma_f32_16x16x32_bf16 v[106:109], v[166:169], v[198:201], v[106:109]
	v_mfma_f32_16x16x32_bf16 v[94:97], v[154:157], v[206:209], v[94:97]
	v_mfma_f32_16x16x32_bf16 v[90:93], v[166:169], v[206:209], v[90:93]
	v_mfma_f32_16x16x32_bf16 v[78:81], v[154:157], v[214:217], v[78:81]
	v_mfma_f32_16x16x32_bf16 v[74:77], v[166:169], v[214:217], v[74:77]
	v_mfma_f32_16x16x32_bf16 v[118:121], v[170:173], v[186:189], v[118:121]
	v_mfma_f32_16x16x32_bf16 v[114:117], v[178:181], v[186:189], v[114:117]
	v_mfma_f32_16x16x32_bf16 v[102:105], v[170:173], v[194:197], v[102:105]
	v_mfma_f32_16x16x32_bf16 v[98:101], v[178:181], v[194:197], v[98:101]
	v_mfma_f32_16x16x32_bf16 v[86:89], v[170:173], v[202:205], v[86:89]
	v_mfma_f32_16x16x32_bf16 v[82:85], v[178:181], v[202:205], v[82:85]
	v_mfma_f32_16x16x32_bf16 v[70:73], v[170:173], v[210:213], v[70:73]
	v_mfma_f32_16x16x32_bf16 v[66:69], v[178:181], v[210:213], v[66:69]
	v_mfma_f32_16x16x32_bf16 v[118:121], v[174:177], v[190:193], v[118:121]
	v_mfma_f32_16x16x32_bf16 v[114:117], v[182:185], v[190:193], v[114:117]
	v_mfma_f32_16x16x32_bf16 v[102:105], v[174:177], v[198:201], v[102:105]
	v_mfma_f32_16x16x32_bf16 v[98:101], v[182:185], v[198:201], v[98:101]
	v_mfma_f32_16x16x32_bf16 v[86:89], v[174:177], v[206:209], v[86:89]
	v_mfma_f32_16x16x32_bf16 v[82:85], v[182:185], v[206:209], v[82:85]
	v_mfma_f32_16x16x32_bf16 v[70:73], v[174:177], v[214:217], v[70:73]
	v_mfma_f32_16x16x32_bf16 v[66:69], v[182:185], v[214:217], v[66:69]
	s_barrier
	s_add_i32 s52, s46, s2
	v_lshl_add_u64 v[162:163], s[30:31], 0, v[132:133]
	s_mov_b32 m0, s52
	ds_read_b128 v[186:189], v151 offset:16384
	ds_read_b128 v[190:193], v151 offset:17408
	ds_read_b128 v[194:197], v151 offset:18432
	ds_read_b128 v[198:201], v151 offset:19456
	ds_read_b128 v[202:205], v151 offset:20480
	ds_read_b128 v[206:209], v151 offset:21504
	ds_read_b128 v[210:213], v151 offset:22528
	ds_read_b128 v[214:217], v151 offset:23552
	global_load_lds_dwordx4 v[162:163], off
	s_add_i32 m0, s52, 0x2000
	s_add_u32 s52, s30, 0x20000
	v_lshl_add_u64 v[218:219], s[30:31], 0, v[136:137]
	s_addc_u32 s53, s31, 0
	s_add_i32 s54, s47, s2
	global_load_lds_dwordx4 v[218:219], off
	v_lshl_add_u64 v[220:221], s[52:53], 0, v[132:133]
	s_mov_b32 m0, s54
	v_lshl_add_u64 v[222:223], s[34:35], 0, v[134:135]
	global_load_lds_dwordx4 v[220:221], off
	v_lshl_add_u64 v[220:221], s[52:53], 0, v[136:137]
	s_add_i32 m0, s54, 0x2000
	s_nop 0
	global_load_lds_dwordx4 v[220:221], off
	v_lshl_add_u64 v[220:221], s[34:35], 0, v[130:131]
	s_mov_b32 m0, s27
	s_nop 0
	global_load_lds_dwordx4 v[220:221], off
	s_mov_b32 m0, s37
	s_nop 0
	global_load_lds_dwordx4 v[222:223], off
	s_waitcnt vmcnt(8)
	s_waitcnt lgkmcnt(0)
	s_barrier
	v_mfma_f32_16x16x32_bf16 v[62:65], v[142:145], v[186:189], v[62:65]
	v_mfma_f32_16x16x32_bf16 v[58:61], v[158:161], v[186:189], v[58:61]
	v_mfma_f32_16x16x32_bf16 v[46:49], v[142:145], v[194:197], v[46:49]
	v_mfma_f32_16x16x32_bf16 v[42:45], v[158:161], v[194:197], v[42:45]
	v_mfma_f32_16x16x32_bf16 v[30:33], v[142:145], v[202:205], v[30:33]
	v_mfma_f32_16x16x32_bf16 v[26:29], v[158:161], v[202:205], v[26:29]
	v_mfma_f32_16x16x32_bf16 v[14:17], v[142:145], v[210:213], v[14:17]
	v_mfma_f32_16x16x32_bf16 v[10:13], v[158:161], v[210:213], v[10:13]
	v_mfma_f32_16x16x32_bf16 v[62:65], v[154:157], v[190:193], v[62:65]
	v_mfma_f32_16x16x32_bf16 v[58:61], v[166:169], v[190:193], v[58:61]
	v_mfma_f32_16x16x32_bf16 v[46:49], v[154:157], v[198:201], v[46:49]
	v_mfma_f32_16x16x32_bf16 v[42:45], v[166:169], v[198:201], v[42:45]
	v_mfma_f32_16x16x32_bf16 v[30:33], v[154:157], v[206:209], v[30:33]
	v_mfma_f32_16x16x32_bf16 v[26:29], v[166:169], v[206:209], v[26:29]
	v_mfma_f32_16x16x32_bf16 v[14:17], v[154:157], v[214:217], v[14:17]
	v_mfma_f32_16x16x32_bf16 v[10:13], v[166:169], v[214:217], v[10:13]
	v_mfma_f32_16x16x32_bf16 v[54:57], v[170:173], v[186:189], v[54:57]
	v_mfma_f32_16x16x32_bf16 v[50:53], v[178:181], v[186:189], v[50:53]
	v_mfma_f32_16x16x32_bf16 v[38:41], v[170:173], v[194:197], v[38:41]
	v_mfma_f32_16x16x32_bf16 v[34:37], v[178:181], v[194:197], v[34:37]
	v_mfma_f32_16x16x32_bf16 v[22:25], v[170:173], v[202:205], v[22:25]
	v_mfma_f32_16x16x32_bf16 v[18:21], v[178:181], v[202:205], v[18:21]
	v_mfma_f32_16x16x32_bf16 v[6:9], v[170:173], v[210:213], v[6:9]
	v_mfma_f32_16x16x32_bf16 v[2:5], v[178:181], v[210:213], v[2:5]
	v_mfma_f32_16x16x32_bf16 v[54:57], v[174:177], v[190:193], v[54:57]
	v_mfma_f32_16x16x32_bf16 v[50:53], v[182:185], v[190:193], v[50:53]
	v_mfma_f32_16x16x32_bf16 v[38:41], v[174:177], v[198:201], v[38:41]
	v_mfma_f32_16x16x32_bf16 v[34:37], v[182:185], v[198:201], v[34:37]
	v_mfma_f32_16x16x32_bf16 v[22:25], v[174:177], v[206:209], v[22:25]
	v_mfma_f32_16x16x32_bf16 v[18:21], v[182:185], v[206:209], v[18:21]
	v_mfma_f32_16x16x32_bf16 v[6:9], v[174:177], v[214:217], v[6:9]
	v_mfma_f32_16x16x32_bf16 v[2:5], v[182:185], v[214:217], v[2:5]
	s_barrier
	s_add_i32 s52, 0, 0x18000
	v_add_u32_e32 v153, s52, v148
	s_add_i32 s53, 0, 0x1c000
	ds_read_b128 v[142:145], v153
	ds_read_b128 v[154:157], v153 offset:1024
	ds_read_b128 v[158:161], v153 offset:2048
	ds_read_b128 v[166:169], v153 offset:3072
	v_add_u32_e32 v153, s53, v148
	ds_read_b128 v[170:173], v153
	ds_read_b128 v[174:177], v153 offset:1024
	ds_read_b128 v[178:181], v153 offset:2048
	ds_read_b128 v[182:185], v153 offset:3072
	s_add_u32 s34, s34, 0x20000
	s_addc_u32 s35, s35, 0
	s_mov_b32 m0, s38
	v_lshl_add_u64 v[224:225], s[34:35], 0, v[130:131]
	ds_read_b128 v[186:189], v151 offset:32768
	ds_read_b128 v[190:193], v151 offset:33792
	ds_read_b128 v[194:197], v151 offset:34816
	ds_read_b128 v[198:201], v151 offset:35840
	ds_read_b128 v[202:205], v151 offset:36864
	ds_read_b128 v[206:209], v151 offset:37888
	ds_read_b128 v[210:213], v151 offset:38912
	ds_read_b128 v[214:217], v151 offset:39936
	global_load_lds_dwordx4 v[224:225], off
	v_lshl_add_u64 v[224:225], s[34:35], 0, v[134:135]
	s_mov_b32 m0, s39
	s_nop 0
	global_load_lds_dwordx4 v[224:225], off
	s_waitcnt vmcnt(8)
	s_waitcnt lgkmcnt(0)
	s_barrier
	v_mfma_f32_16x16x32_bf16 v[126:129], v[142:145], v[186:189], v[126:129]
	v_mfma_f32_16x16x32_bf16 v[122:125], v[158:161], v[186:189], v[122:125]
	v_mfma_f32_16x16x32_bf16 v[110:113], v[142:145], v[194:197], v[110:113]
	v_mfma_f32_16x16x32_bf16 v[106:109], v[158:161], v[194:197], v[106:109]
	v_mfma_f32_16x16x32_bf16 v[94:97], v[142:145], v[202:205], v[94:97]
	v_mfma_f32_16x16x32_bf16 v[90:93], v[158:161], v[202:205], v[90:93]
	v_mfma_f32_16x16x32_bf16 v[78:81], v[142:145], v[210:213], v[78:81]
	v_mfma_f32_16x16x32_bf16 v[74:77], v[158:161], v[210:213], v[74:77]
	v_mfma_f32_16x16x32_bf16 v[126:129], v[154:157], v[190:193], v[126:129]
	v_mfma_f32_16x16x32_bf16 v[122:125], v[166:169], v[190:193], v[122:125]
	v_mfma_f32_16x16x32_bf16 v[110:113], v[154:157], v[198:201], v[110:113]
	v_mfma_f32_16x16x32_bf16 v[106:109], v[166:169], v[198:201], v[106:109]
	v_mfma_f32_16x16x32_bf16 v[94:97], v[154:157], v[206:209], v[94:97]
	v_mfma_f32_16x16x32_bf16 v[90:93], v[166:169], v[206:209], v[90:93]
	v_mfma_f32_16x16x32_bf16 v[78:81], v[154:157], v[214:217], v[78:81]
	v_mfma_f32_16x16x32_bf16 v[74:77], v[166:169], v[214:217], v[74:77]
	v_mfma_f32_16x16x32_bf16 v[118:121], v[170:173], v[186:189], v[118:121]
	v_mfma_f32_16x16x32_bf16 v[114:117], v[178:181], v[186:189], v[114:117]
	v_mfma_f32_16x16x32_bf16 v[102:105], v[170:173], v[194:197], v[102:105]
	v_mfma_f32_16x16x32_bf16 v[98:101], v[178:181], v[194:197], v[98:101]
	v_mfma_f32_16x16x32_bf16 v[86:89], v[170:173], v[202:205], v[86:89]
	v_mfma_f32_16x16x32_bf16 v[82:85], v[178:181], v[202:205], v[82:85]
	v_mfma_f32_16x16x32_bf16 v[70:73], v[170:173], v[210:213], v[70:73]
	v_mfma_f32_16x16x32_bf16 v[66:69], v[178:181], v[210:213], v[66:69]
	v_mfma_f32_16x16x32_bf16 v[118:121], v[174:177], v[190:193], v[118:121]
	v_mfma_f32_16x16x32_bf16 v[114:117], v[182:185], v[190:193], v[114:117]
	v_mfma_f32_16x16x32_bf16 v[102:105], v[174:177], v[198:201], v[102:105]
	v_mfma_f32_16x16x32_bf16 v[98:101], v[182:185], v[198:201], v[98:101]
	v_mfma_f32_16x16x32_bf16 v[86:89], v[174:177], v[206:209], v[86:89]
	v_mfma_f32_16x16x32_bf16 v[82:85], v[182:185], v[206:209], v[82:85]
	v_mfma_f32_16x16x32_bf16 v[70:73], v[174:177], v[214:217], v[70:73]
	v_mfma_f32_16x16x32_bf16 v[66:69], v[182:185], v[214:217], v[66:69]
	s_barrier
	s_add_i32 s34, s52, s2
	v_lshl_add_u64 v[162:163], v[162:163], 0, s[10:11]
	s_mov_b32 m0, s34
	ds_read_b128 v[186:189], v151 offset:49152
	ds_read_b128 v[190:193], v151 offset:50176
	ds_read_b128 v[194:197], v151 offset:51200
	ds_read_b128 v[198:201], v151 offset:52224
	ds_read_b128 v[202:205], v151 offset:53248
	ds_read_b128 v[206:209], v151 offset:54272
	ds_read_b128 v[210:213], v151 offset:55296
	ds_read_b128 v[214:217], v151 offset:56320
	global_load_lds_dwordx4 v[162:163], off
	s_add_i32 m0, s34, 0x2000
	s_add_u32 s30, s30, 0x20080
	v_lshl_add_u64 v[162:163], v[218:219], 0, s[10:11]
	s_addc_u32 s31, s31, 0
	s_add_i32 s34, s53, s2
	global_load_lds_dwordx4 v[162:163], off
	v_lshl_add_u64 v[162:163], s[30:31], 0, v[132:133]
	s_mov_b32 m0, s34
	s_nop 0
	global_load_lds_dwordx4 v[162:163], off
	v_lshl_add_u64 v[162:163], s[30:31], 0, v[136:137]
	s_add_i32 m0, s34, 0x2000
	s_nop 0
	global_load_lds_dwordx4 v[162:163], off
	v_lshl_add_u64 v[162:163], v[220:221], 0, s[10:11]
	s_mov_b32 m0, s43
	s_nop 0
	global_load_lds_dwordx4 v[162:163], off
	v_lshl_add_u64 v[162:163], v[222:223], 0, s[10:11]
	s_mov_b32 m0, s44
	s_nop 0
	global_load_lds_dwordx4 v[162:163], off
	s_waitcnt vmcnt(8)
	s_waitcnt lgkmcnt(0)
	s_barrier
	v_mfma_f32_16x16x32_bf16 v[62:65], v[142:145], v[186:189], v[62:65]
	v_mfma_f32_16x16x32_bf16 v[58:61], v[158:161], v[186:189], v[58:61]
	v_mfma_f32_16x16x32_bf16 v[46:49], v[142:145], v[194:197], v[46:49]
	v_mfma_f32_16x16x32_bf16 v[42:45], v[158:161], v[194:197], v[42:45]
	v_mfma_f32_16x16x32_bf16 v[30:33], v[142:145], v[202:205], v[30:33]
	v_mfma_f32_16x16x32_bf16 v[26:29], v[158:161], v[202:205], v[26:29]
	v_mfma_f32_16x16x32_bf16 v[14:17], v[142:145], v[210:213], v[14:17]
	v_mfma_f32_16x16x32_bf16 v[10:13], v[158:161], v[210:213], v[10:13]
	v_mfma_f32_16x16x32_bf16 v[62:65], v[154:157], v[190:193], v[62:65]
	v_mfma_f32_16x16x32_bf16 v[58:61], v[166:169], v[190:193], v[58:61]
	v_mfma_f32_16x16x32_bf16 v[46:49], v[154:157], v[198:201], v[46:49]
	v_mfma_f32_16x16x32_bf16 v[42:45], v[166:169], v[198:201], v[42:45]
	v_mfma_f32_16x16x32_bf16 v[30:33], v[154:157], v[206:209], v[30:33]
	v_mfma_f32_16x16x32_bf16 v[26:29], v[166:169], v[206:209], v[26:29]
	v_mfma_f32_16x16x32_bf16 v[14:17], v[154:157], v[214:217], v[14:17]
	v_mfma_f32_16x16x32_bf16 v[10:13], v[166:169], v[214:217], v[10:13]
	v_mfma_f32_16x16x32_bf16 v[54:57], v[170:173], v[186:189], v[54:57]
	v_mfma_f32_16x16x32_bf16 v[50:53], v[178:181], v[186:189], v[50:53]
	v_mfma_f32_16x16x32_bf16 v[38:41], v[170:173], v[194:197], v[38:41]
	v_mfma_f32_16x16x32_bf16 v[34:37], v[178:181], v[194:197], v[34:37]
	v_mfma_f32_16x16x32_bf16 v[22:25], v[170:173], v[202:205], v[22:25]
	v_mfma_f32_16x16x32_bf16 v[18:21], v[178:181], v[202:205], v[18:21]
	v_mfma_f32_16x16x32_bf16 v[6:9], v[170:173], v[210:213], v[6:9]
	v_mfma_f32_16x16x32_bf16 v[2:5], v[178:181], v[210:213], v[2:5]
	v_mfma_f32_16x16x32_bf16 v[54:57], v[174:177], v[190:193], v[54:57]
	v_mfma_f32_16x16x32_bf16 v[50:53], v[182:185], v[190:193], v[50:53]
	v_mfma_f32_16x16x32_bf16 v[38:41], v[174:177], v[198:201], v[38:41]
	v_mfma_f32_16x16x32_bf16 v[34:37], v[182:185], v[198:201], v[34:37]
	v_mfma_f32_16x16x32_bf16 v[22:25], v[174:177], v[206:209], v[22:25]
	v_mfma_f32_16x16x32_bf16 v[18:21], v[182:185], v[206:209], v[18:21]
	v_mfma_f32_16x16x32_bf16 v[6:9], v[174:177], v[214:217], v[6:9]
	v_mfma_f32_16x16x32_bf16 v[2:5], v[182:185], v[214:217], v[2:5]
	s_barrier
	s_add_i32 s51, s51, 2
	s_add_u32 s28, s28, 0x100
	s_addc_u32 s29, s29, 0
	s_add_u32 s49, s49, 0x100
	s_addc_u32 s50, s50, 0
	s_cmp_gt_u32 s51, 5
	s_cbranch_scc0 .LBB0_1220
	s_setprio 0
	s_lshl_b32 s98, s26, 8
	s_add_i32 s98, s98, s41
	v_add_u32_e32 v240, s98, v146
	s_lshl_b32 s98, s0, 8
	s_or_b32 s98, s98, s42
	v_lshl_add_u32 v241, v147, 3, s98
	v_lshlrev_b32_e32 v240, 12, v240
	v_lshl_add_u32 v240, v241, 1, v240
	global_load_dwordx4 v[168:171], v240, s[62:63]
	global_load_dwordx4 v[172:175], v240, s[62:63] offset:256
	v_add_u32_e32 v240, 0x10000, v240
	global_load_dwordx4 v[176:179], v240, s[62:63]
	global_load_dwordx4 v[180:183], v240, s[62:63] offset:256
	v_add_u32_e32 v240, 0x10000, v240
	global_load_dwordx4 v[184:187], v240, s[62:63]
	global_load_dwordx4 v[188:191], v240, s[62:63] offset:256
	v_add_u32_e32 v240, 0x10000, v240
	global_load_dwordx4 v[192:195], v240, s[62:63]
	global_load_dwordx4 v[196:199], v240, s[62:63] offset:256
	v_add_u32_e32 v240, 0x50000, v240
	global_load_dwordx4 v[200:203], v240, s[62:63]
	global_load_dwordx4 v[204:207], v240, s[62:63] offset:256
	v_add_u32_e32 v240, 0x10000, v240
	global_load_dwordx4 v[208:211], v240, s[62:63]
	global_load_dwordx4 v[212:215], v240, s[62:63] offset:256
	v_add_u32_e32 v240, 0x10000, v240
	global_load_dwordx4 v[216:219], v240, s[62:63]
	global_load_dwordx4 v[220:223], v240, s[62:63] offset:256
	v_add_u32_e32 v240, 0x10000, v240
	global_load_dwordx4 v[224:227], v240, s[62:63]
	global_load_dwordx4 v[232:235], v240, s[62:63] offset:256
	s_and_b64 vcc, exec, s[12:13]
	s_cbranch_vccz .LBB0_1223
	s_barrier

.Lsp_p10:
.LBB0_1337:
	ds_read_b128 v[142:145], v149
	ds_read_b128 v[154:157], v149 offset:1024
	ds_read_b128 v[158:161], v149 offset:2048
	ds_read_b128 v[166:169], v149 offset:3072
	ds_read_b128 v[170:173], v150
	ds_read_b128 v[174:177], v150 offset:1024
	ds_read_b128 v[178:181], v150 offset:2048
	ds_read_b128 v[182:185], v150 offset:3072
	s_add_u32 s30, s28, 0xfff80080
	s_addc_u32 s31, s29, -1
	s_cmp_eq_u32 s54, 28
	s_cselect_b32 s35, s17, s31
	s_cselect_b32 s34, s19, s30
	s_cselect_b32 s31, s50, s53
	s_cselect_b32 s30, s51, s52
	v_lshl_add_u64 v[162:163], s[28:29], 0, v[138:139]
	s_add_i32 m0, s25, 0xc000
	ds_read_b128 v[186:189], v151
	ds_read_b128 v[190:193], v151 offset:1024
	ds_read_b128 v[194:197], v151 offset:2048
	ds_read_b128 v[198:201], v151 offset:3072
	ds_read_b128 v[202:205], v151 offset:4096
	ds_read_b128 v[206:209], v151 offset:5120
	ds_read_b128 v[210:213], v151 offset:6144
	ds_read_b128 v[214:217], v151 offset:7168
	global_load_lds_dwordx4 v[162:163], off
	v_lshl_add_u64 v[162:163], s[28:29], 0, v[140:141]
	s_add_i32 m0, s25, 0xe000
	s_nop 0
	global_load_lds_dwordx4 v[162:163], off
	s_waitcnt vmcnt(8)
	s_waitcnt lgkmcnt(0)
	s_barrier
	v_mfma_f32_16x16x32_bf16 v[122:125], v[142:145], v[186:189], v[122:125]
	v_mfma_f32_16x16x32_bf16 v[114:117], v[158:161], v[186:189], v[114:117]
	v_mfma_f32_16x16x32_bf16 v[106:109], v[142:145], v[194:197], v[106:109]
	v_mfma_f32_16x16x32_bf16 v[98:101], v[158:161], v[194:197], v[98:101]
	v_mfma_f32_16x16x32_bf16 v[90:93], v[142:145], v[202:205], v[90:93]
	v_mfma_f32_16x16x32_bf16 v[82:85], v[158:161], v[202:205], v[82:85]
	v_mfma_f32_16x16x32_bf16 v[74:77], v[142:145], v[210:213], v[74:77]
	v_mfma_f32_16x16x32_bf16 v[66:69], v[158:161], v[210:213], v[66:69]
	v_mfma_f32_16x16x32_bf16 v[122:125], v[154:157], v[190:193], v[122:125]
	v_mfma_f32_16x16x32_bf16 v[114:117], v[166:169], v[190:193], v[114:117]
	v_mfma_f32_16x16x32_bf16 v[106:109], v[154:157], v[198:201], v[106:109]
	v_mfma_f32_16x16x32_bf16 v[98:101], v[166:169], v[198:201], v[98:101]
	v_mfma_f32_16x16x32_bf16 v[90:93], v[154:157], v[206:209], v[90:93]
	v_mfma_f32_16x16x32_bf16 v[82:85], v[166:169], v[206:209], v[82:85]
	v_mfma_f32_16x16x32_bf16 v[74:77], v[154:157], v[214:217], v[74:77]
	v_mfma_f32_16x16x32_bf16 v[66:69], v[166:169], v[214:217], v[66:69]
	v_mfma_f32_16x16x32_bf16 v[126:129], v[170:173], v[186:189], v[126:129]
	v_mfma_f32_16x16x32_bf16 v[118:121], v[178:181], v[186:189], v[118:121]
	v_mfma_f32_16x16x32_bf16 v[110:113], v[170:173], v[194:197], v[110:113]
	v_mfma_f32_16x16x32_bf16 v[102:105], v[178:181], v[194:197], v[102:105]
	v_mfma_f32_16x16x32_bf16 v[94:97], v[170:173], v[202:205], v[94:97]
	v_mfma_f32_16x16x32_bf16 v[86:89], v[178:181], v[202:205], v[86:89]
	v_mfma_f32_16x16x32_bf16 v[78:81], v[170:173], v[210:213], v[78:81]
	v_mfma_f32_16x16x32_bf16 v[70:73], v[178:181], v[210:213], v[70:73]
	v_mfma_f32_16x16x32_bf16 v[126:129], v[174:177], v[190:193], v[126:129]
	v_mfma_f32_16x16x32_bf16 v[118:121], v[182:185], v[190:193], v[118:121]
	v_mfma_f32_16x16x32_bf16 v[110:113], v[174:177], v[198:201], v[110:113]
	v_mfma_f32_16x16x32_bf16 v[102:105], v[182:185], v[198:201], v[102:105]
	v_mfma_f32_16x16x32_bf16 v[94:97], v[174:177], v[206:209], v[94:97]
	v_mfma_f32_16x16x32_bf16 v[86:89], v[182:185], v[206:209], v[86:89]
	v_mfma_f32_16x16x32_bf16 v[78:81], v[174:177], v[214:217], v[78:81]
	v_mfma_f32_16x16x32_bf16 v[70:73], v[182:185], v[214:217], v[70:73]
	s_barrier
	s_add_i32 s55, s46, s36
	v_lshl_add_u64 v[162:163], s[30:31], 0, v[132:133]
	s_mov_b32 m0, s55
	ds_read_b128 v[186:189], v151 offset:16384
	ds_read_b128 v[190:193], v151 offset:17408
	ds_read_b128 v[194:197], v151 offset:18432
	ds_read_b128 v[198:201], v151 offset:19456
	ds_read_b128 v[202:205], v151 offset:20480
	ds_read_b128 v[206:209], v151 offset:21504
	ds_read_b128 v[210:213], v151 offset:22528
	ds_read_b128 v[214:217], v151 offset:23552
	global_load_lds_dwordx4 v[162:163], off
	s_add_i32 m0, s55, 0x2000
	s_add_u32 s56, s30, 0x80000
	v_lshl_add_u64 v[218:219], s[30:31], 0, v[136:137]
	s_addc_u32 s57, s31, 0
	s_add_i32 s55, s47, s36
	global_load_lds_dwordx4 v[218:219], off
	v_lshl_add_u64 v[220:221], s[56:57], 0, v[132:133]
	s_mov_b32 m0, s55
	v_lshl_add_u64 v[222:223], s[34:35], 0, v[134:135]
	global_load_lds_dwordx4 v[220:221], off
	v_lshl_add_u64 v[220:221], s[56:57], 0, v[136:137]
	s_add_i32 m0, s55, 0x2000
	s_nop 0
	global_load_lds_dwordx4 v[220:221], off
	v_lshl_add_u64 v[220:221], s[34:35], 0, v[130:131]
	s_mov_b32 m0, s25
	s_nop 0
	global_load_lds_dwordx4 v[220:221], off
	s_mov_b32 m0, s27
	s_nop 0
	global_load_lds_dwordx4 v[222:223], off
	s_waitcnt vmcnt(8)
	s_waitcnt lgkmcnt(0)
	s_barrier
	v_mfma_f32_16x16x32_bf16 v[58:61], v[142:145], v[186:189], v[58:61]
	v_mfma_f32_16x16x32_bf16 v[50:53], v[158:161], v[186:189], v[50:53]
	v_mfma_f32_16x16x32_bf16 v[42:45], v[142:145], v[194:197], v[42:45]
	v_mfma_f32_16x16x32_bf16 v[34:37], v[158:161], v[194:197], v[34:37]
	v_mfma_f32_16x16x32_bf16 v[26:29], v[142:145], v[202:205], v[26:29]
	v_mfma_f32_16x16x32_bf16 v[18:21], v[158:161], v[202:205], v[18:21]
	v_mfma_f32_16x16x32_bf16 v[10:13], v[142:145], v[210:213], v[10:13]
	v_mfma_f32_16x16x32_bf16 v[2:5], v[158:161], v[210:213], v[2:5]
	v_mfma_f32_16x16x32_bf16 v[58:61], v[154:157], v[190:193], v[58:61]
	v_mfma_f32_16x16x32_bf16 v[50:53], v[166:169], v[190:193], v[50:53]
	v_mfma_f32_16x16x32_bf16 v[42:45], v[154:157], v[198:201], v[42:45]
	v_mfma_f32_16x16x32_bf16 v[34:37], v[166:169], v[198:201], v[34:37]
	v_mfma_f32_16x16x32_bf16 v[26:29], v[154:157], v[206:209], v[26:29]
	v_mfma_f32_16x16x32_bf16 v[18:21], v[166:169], v[206:209], v[18:21]
	v_mfma_f32_16x16x32_bf16 v[10:13], v[154:157], v[214:217], v[10:13]
	v_mfma_f32_16x16x32_bf16 v[2:5], v[166:169], v[214:217], v[2:5]
	v_mfma_f32_16x16x32_bf16 v[62:65], v[170:173], v[186:189], v[62:65]
	v_mfma_f32_16x16x32_bf16 v[54:57], v[178:181], v[186:189], v[54:57]
	v_mfma_f32_16x16x32_bf16 v[46:49], v[170:173], v[194:197], v[46:49]
	v_mfma_f32_16x16x32_bf16 v[38:41], v[178:181], v[194:197], v[38:41]
	v_mfma_f32_16x16x32_bf16 v[30:33], v[170:173], v[202:205], v[30:33]
	v_mfma_f32_16x16x32_bf16 v[22:25], v[178:181], v[202:205], v[22:25]
	v_mfma_f32_16x16x32_bf16 v[14:17], v[170:173], v[210:213], v[14:17]
	v_mfma_f32_16x16x32_bf16 v[6:9], v[178:181], v[210:213], v[6:9]
	v_mfma_f32_16x16x32_bf16 v[62:65], v[174:177], v[190:193], v[62:65]
	v_mfma_f32_16x16x32_bf16 v[54:57], v[182:185], v[190:193], v[54:57]
	v_mfma_f32_16x16x32_bf16 v[46:49], v[174:177], v[198:201], v[46:49]
	v_mfma_f32_16x16x32_bf16 v[38:41], v[182:185], v[198:201], v[38:41]
	v_mfma_f32_16x16x32_bf16 v[30:33], v[174:177], v[206:209], v[30:33]
	v_mfma_f32_16x16x32_bf16 v[22:25], v[182:185], v[206:209], v[22:25]
	v_mfma_f32_16x16x32_bf16 v[14:17], v[174:177], v[214:217], v[14:17]
	v_mfma_f32_16x16x32_bf16 v[6:9], v[182:185], v[214:217], v[6:9]
	s_barrier
	s_add_i32 s55, 0, 0x18000
	v_add_u32_e32 v153, s55, v148
	s_add_i32 s56, 0, 0x1c000
	ds_read_b128 v[142:145], v153
	ds_read_b128 v[154:157], v153 offset:1024
	ds_read_b128 v[158:161], v153 offset:2048
	ds_read_b128 v[166:169], v153 offset:3072
	v_add_u32_e32 v153, s56, v148
	ds_read_b128 v[170:173], v153
	ds_read_b128 v[174:177], v153 offset:1024
	ds_read_b128 v[178:181], v153 offset:2048
	ds_read_b128 v[182:185], v153 offset:3072
	s_add_u32 s34, s34, 0x80000
	s_addc_u32 s35, s35, 0
	s_mov_b32 m0, s37
	v_lshl_add_u64 v[224:225], s[34:35], 0, v[130:131]
	ds_read_b128 v[186:189], v151 offset:32768
	ds_read_b128 v[190:193], v151 offset:33792
	ds_read_b128 v[194:197], v151 offset:34816
	ds_read_b128 v[198:201], v151 offset:35840
	ds_read_b128 v[202:205], v151 offset:36864
	ds_read_b128 v[206:209], v151 offset:37888
	ds_read_b128 v[210:213], v151 offset:38912
	ds_read_b128 v[214:217], v151 offset:39936
	global_load_lds_dwordx4 v[224:225], off
	v_lshl_add_u64 v[224:225], s[34:35], 0, v[134:135]
	s_mov_b32 m0, s38
	s_nop 0
	global_load_lds_dwordx4 v[224:225], off
	s_waitcnt vmcnt(8)
	s_waitcnt lgkmcnt(0)
	s_barrier
	v_mfma_f32_16x16x32_bf16 v[122:125], v[142:145], v[186:189], v[122:125]
	v_mfma_f32_16x16x32_bf16 v[114:117], v[158:161], v[186:189], v[114:117]
	v_mfma_f32_16x16x32_bf16 v[106:109], v[142:145], v[194:197], v[106:109]
	v_mfma_f32_16x16x32_bf16 v[98:101], v[158:161], v[194:197], v[98:101]
	v_mfma_f32_16x16x32_bf16 v[90:93], v[142:145], v[202:205], v[90:93]
	v_mfma_f32_16x16x32_bf16 v[82:85], v[158:161], v[202:205], v[82:85]
	v_mfma_f32_16x16x32_bf16 v[74:77], v[142:145], v[210:213], v[74:77]
	v_mfma_f32_16x16x32_bf16 v[66:69], v[158:161], v[210:213], v[66:69]
	v_mfma_f32_16x16x32_bf16 v[122:125], v[154:157], v[190:193], v[122:125]
	v_mfma_f32_16x16x32_bf16 v[114:117], v[166:169], v[190:193], v[114:117]
	v_mfma_f32_16x16x32_bf16 v[106:109], v[154:157], v[198:201], v[106:109]
	v_mfma_f32_16x16x32_bf16 v[98:101], v[166:169], v[198:201], v[98:101]
	v_mfma_f32_16x16x32_bf16 v[90:93], v[154:157], v[206:209], v[90:93]
	v_mfma_f32_16x16x32_bf16 v[82:85], v[166:169], v[206:209], v[82:85]
	v_mfma_f32_16x16x32_bf16 v[74:77], v[154:157], v[214:217], v[74:77]
	v_mfma_f32_16x16x32_bf16 v[66:69], v[166:169], v[214:217], v[66:69]
	v_mfma_f32_16x16x32_bf16 v[126:129], v[170:173], v[186:189], v[126:129]
	v_mfma_f32_16x16x32_bf16 v[118:121], v[178:181], v[186:189], v[118:121]
	v_mfma_f32_16x16x32_bf16 v[110:113], v[170:173], v[194:197], v[110:113]
	v_mfma_f32_16x16x32_bf16 v[102:105], v[178:181], v[194:197], v[102:105]
	v_mfma_f32_16x16x32_bf16 v[94:97], v[170:173], v[202:205], v[94:97]
	v_mfma_f32_16x16x32_bf16 v[86:89], v[178:181], v[202:205], v[86:89]
	v_mfma_f32_16x16x32_bf16 v[78:81], v[170:173], v[210:213], v[78:81]
	v_mfma_f32_16x16x32_bf16 v[70:73], v[178:181], v[210:213], v[70:73]
	v_mfma_f32_16x16x32_bf16 v[126:129], v[174:177], v[190:193], v[126:129]
	v_mfma_f32_16x16x32_bf16 v[118:121], v[182:185], v[190:193], v[118:121]
	v_mfma_f32_16x16x32_bf16 v[110:113], v[174:177], v[198:201], v[110:113]
	v_mfma_f32_16x16x32_bf16 v[102:105], v[182:185], v[198:201], v[102:105]
	v_mfma_f32_16x16x32_bf16 v[94:97], v[174:177], v[206:209], v[94:97]
	v_mfma_f32_16x16x32_bf16 v[86:89], v[182:185], v[206:209], v[86:89]
	v_mfma_f32_16x16x32_bf16 v[78:81], v[174:177], v[214:217], v[78:81]
	v_mfma_f32_16x16x32_bf16 v[70:73], v[182:185], v[214:217], v[70:73]
	s_barrier
	s_add_i32 s34, s55, s36
	v_lshl_add_u64 v[162:163], v[162:163], 0, s[12:13]
	s_mov_b32 m0, s34
	ds_read_b128 v[186:189], v151 offset:49152
	ds_read_b128 v[190:193], v151 offset:50176
	ds_read_b128 v[194:197], v151 offset:51200
	ds_read_b128 v[198:201], v151 offset:52224
	ds_read_b128 v[202:205], v151 offset:53248
	ds_read_b128 v[206:209], v151 offset:54272
	ds_read_b128 v[210:213], v151 offset:55296
	ds_read_b128 v[214:217], v151 offset:56320
	global_load_lds_dwordx4 v[162:163], off
	s_add_i32 m0, s34, 0x2000
	s_add_u32 s30, s30, 0x80080
	v_lshl_add_u64 v[162:163], v[218:219], 0, s[12:13]
	s_addc_u32 s31, s31, 0
	s_add_i32 s34, s56, s36
	global_load_lds_dwordx4 v[162:163], off
	v_lshl_add_u64 v[162:163], s[30:31], 0, v[132:133]
	s_mov_b32 m0, s34
	s_nop 0
	global_load_lds_dwordx4 v[162:163], off
	v_lshl_add_u64 v[162:163], s[30:31], 0, v[136:137]
	s_add_i32 m0, s34, 0x2000
	s_nop 0
	global_load_lds_dwordx4 v[162:163], off
	v_lshl_add_u64 v[162:163], v[220:221], 0, s[12:13]
	s_mov_b32 m0, s42
	s_nop 0
	global_load_lds_dwordx4 v[162:163], off
	v_lshl_add_u64 v[162:163], v[222:223], 0, s[12:13]
	s_mov_b32 m0, s43
	s_nop 0
	global_load_lds_dwordx4 v[162:163], off
	s_waitcnt vmcnt(8)
	s_waitcnt lgkmcnt(0)
	s_barrier
	v_mfma_f32_16x16x32_bf16 v[58:61], v[142:145], v[186:189], v[58:61]
	v_mfma_f32_16x16x32_bf16 v[50:53], v[158:161], v[186:189], v[50:53]
	v_mfma_f32_16x16x32_bf16 v[42:45], v[142:145], v[194:197], v[42:45]
	v_mfma_f32_16x16x32_bf16 v[34:37], v[158:161], v[194:197], v[34:37]
	v_mfma_f32_16x16x32_bf16 v[26:29], v[142:145], v[202:205], v[26:29]
	v_mfma_f32_16x16x32_bf16 v[18:21], v[158:161], v[202:205], v[18:21]
	v_mfma_f32_16x16x32_bf16 v[10:13], v[142:145], v[210:213], v[10:13]
	v_mfma_f32_16x16x32_bf16 v[2:5], v[158:161], v[210:213], v[2:5]
	v_mfma_f32_16x16x32_bf16 v[58:61], v[154:157], v[190:193], v[58:61]
	v_mfma_f32_16x16x32_bf16 v[50:53], v[166:169], v[190:193], v[50:53]
	v_mfma_f32_16x16x32_bf16 v[42:45], v[154:157], v[198:201], v[42:45]
	v_mfma_f32_16x16x32_bf16 v[34:37], v[166:169], v[198:201], v[34:37]
	v_mfma_f32_16x16x32_bf16 v[26:29], v[154:157], v[206:209], v[26:29]
	v_mfma_f32_16x16x32_bf16 v[18:21], v[166:169], v[206:209], v[18:21]
	v_mfma_f32_16x16x32_bf16 v[10:13], v[154:157], v[214:217], v[10:13]
	v_mfma_f32_16x16x32_bf16 v[2:5], v[166:169], v[214:217], v[2:5]
	v_mfma_f32_16x16x32_bf16 v[62:65], v[170:173], v[186:189], v[62:65]
	v_mfma_f32_16x16x32_bf16 v[54:57], v[178:181], v[186:189], v[54:57]
	v_mfma_f32_16x16x32_bf16 v[46:49], v[170:173], v[194:197], v[46:49]
	v_mfma_f32_16x16x32_bf16 v[38:41], v[178:181], v[194:197], v[38:41]
	v_mfma_f32_16x16x32_bf16 v[30:33], v[170:173], v[202:205], v[30:33]
	v_mfma_f32_16x16x32_bf16 v[22:25], v[178:181], v[202:205], v[22:25]
	v_mfma_f32_16x16x32_bf16 v[14:17], v[170:173], v[210:213], v[14:17]
	v_mfma_f32_16x16x32_bf16 v[6:9], v[178:181], v[210:213], v[6:9]
	v_mfma_f32_16x16x32_bf16 v[62:65], v[174:177], v[190:193], v[62:65]
	v_mfma_f32_16x16x32_bf16 v[54:57], v[182:185], v[190:193], v[54:57]
	v_mfma_f32_16x16x32_bf16 v[46:49], v[174:177], v[198:201], v[46:49]
	v_mfma_f32_16x16x32_bf16 v[38:41], v[182:185], v[198:201], v[38:41]
	v_mfma_f32_16x16x32_bf16 v[30:33], v[174:177], v[206:209], v[30:33]
	v_mfma_f32_16x16x32_bf16 v[22:25], v[182:185], v[206:209], v[22:25]
	v_mfma_f32_16x16x32_bf16 v[14:17], v[174:177], v[214:217], v[14:17]
	v_mfma_f32_16x16x32_bf16 v[6:9], v[182:185], v[214:217], v[6:9]
	s_barrier
	s_add_i32 s54, s54, 2
	s_add_u32 s28, s28, 0x100
	s_addc_u32 s29, s29, 0
	s_add_u32 s52, s52, 0x100
	s_addc_u32 s53, s53, 0
	s_cmp_gt_u32 s54, 29
	s_cbranch_scc0 .LBB0_1337
	s_setprio 0
	v_mov_b32_e32 v142, v1
	v_mov_b32_e32 v153, v147
	v_mov_b32_e32 v143, v165
	v_mov_b32_e32 v144, v146
	s_lshl_b32 s17, s26, 8
	s_add_i32 s17, s17, s40
	v_add_u32_e32 v142, s17, v144
	v_ashrrev_i32_e32 v143, 31, v142
	v_lshl_add_u64 v[144:145], v[142:143], 2, s[10:11]
	global_load_dword v229, v[144:145], off
	global_load_dword v230, v[144:145], off offset:64
	global_load_dword v231, v[144:145], off offset:128
	global_load_dword v232, v[144:145], off offset:192
	global_load_dword v233, v[144:145], off offset:512
	global_load_dword v234, v[144:145], off offset:576
	global_load_dword v235, v[144:145], off offset:640
	global_load_dword v236, v[144:145], off offset:704
	s_and_b64 vcc, exec, s[14:15]
	s_cbranch_vccz .LBB0_1340
	s_barrier

.Lsp_p11:
.LBB0_1449:
	ds_read_b128 v[140:143], v167
	ds_read_b128 v[144:147], v167 offset:1024
	ds_read_b128 v[148:151], v167 offset:2048
	ds_read_b128 v[152:155], v167 offset:3072
	ds_read_b128 v[156:159], v168
	ds_read_b128 v[172:175], v168 offset:1024
	ds_read_b128 v[176:179], v168 offset:2048
	ds_read_b128 v[180:183], v168 offset:3072
	s_add_u32 s20, s0, 0xffea0080
	s_addc_u32 s21, s1, -1
	s_cmpk_eq_i32 s52, 0x54
	s_cselect_b32 s23, s25, s21
	s_cselect_b32 s22, s47, s20
	s_cselect_b32 s21, s48, s51
	s_cselect_b32 s20, s49, s50
	v_lshl_add_u64 v[160:161], s[0:1], 0, v[136:137]
	s_add_i32 m0, s29, 0xc000
	ds_read_b128 v[184:187], v169
	ds_read_b128 v[188:191], v169 offset:1024
	ds_read_b128 v[192:195], v169 offset:2048
	ds_read_b128 v[196:199], v169 offset:3072
	ds_read_b128 v[200:203], v169 offset:4096
	ds_read_b128 v[204:207], v169 offset:5120
	ds_read_b128 v[208:211], v169 offset:6144
	ds_read_b128 v[212:215], v169 offset:7168
	global_load_lds_dwordx4 v[160:161], off
	v_lshl_add_u64 v[160:161], s[0:1], 0, v[138:139]
	s_add_i32 m0, s29, 0xe000
	s_nop 0
	global_load_lds_dwordx4 v[160:161], off
	s_waitcnt vmcnt(8)
	s_waitcnt lgkmcnt(0)
	s_barrier
	v_mfma_f32_16x16x32_bf16 v[124:127], v[140:143], v[184:187], v[124:127]
	v_mfma_f32_16x16x32_bf16 v[120:123], v[148:151], v[184:187], v[120:123]
	v_mfma_f32_16x16x32_bf16 v[108:111], v[140:143], v[192:195], v[108:111]
	v_mfma_f32_16x16x32_bf16 v[104:107], v[148:151], v[192:195], v[104:107]
	v_mfma_f32_16x16x32_bf16 v[92:95], v[140:143], v[200:203], v[92:95]
	v_mfma_f32_16x16x32_bf16 v[88:91], v[148:151], v[200:203], v[88:91]
	v_mfma_f32_16x16x32_bf16 v[76:79], v[140:143], v[208:211], v[76:79]
	v_mfma_f32_16x16x32_bf16 v[72:75], v[148:151], v[208:211], v[72:75]
	v_mfma_f32_16x16x32_bf16 v[124:127], v[144:147], v[188:191], v[124:127]
	v_mfma_f32_16x16x32_bf16 v[120:123], v[152:155], v[188:191], v[120:123]
	v_mfma_f32_16x16x32_bf16 v[108:111], v[144:147], v[196:199], v[108:111]
	v_mfma_f32_16x16x32_bf16 v[104:107], v[152:155], v[196:199], v[104:107]
	v_mfma_f32_16x16x32_bf16 v[92:95], v[144:147], v[204:207], v[92:95]
	v_mfma_f32_16x16x32_bf16 v[88:91], v[152:155], v[204:207], v[88:91]
	v_mfma_f32_16x16x32_bf16 v[76:79], v[144:147], v[212:215], v[76:79]
	v_mfma_f32_16x16x32_bf16 v[72:75], v[152:155], v[212:215], v[72:75]
	v_mfma_f32_16x16x32_bf16 v[116:119], v[156:159], v[184:187], v[116:119]
	v_mfma_f32_16x16x32_bf16 v[112:115], v[176:179], v[184:187], v[112:115]
	v_mfma_f32_16x16x32_bf16 v[100:103], v[156:159], v[192:195], v[100:103]
	v_mfma_f32_16x16x32_bf16 v[96:99], v[176:179], v[192:195], v[96:99]
	v_mfma_f32_16x16x32_bf16 v[84:87], v[156:159], v[200:203], v[84:87]
	v_mfma_f32_16x16x32_bf16 v[80:83], v[176:179], v[200:203], v[80:83]
	v_mfma_f32_16x16x32_bf16 v[68:71], v[156:159], v[208:211], v[68:71]
	v_mfma_f32_16x16x32_bf16 v[64:67], v[176:179], v[208:211], v[64:67]
	v_mfma_f32_16x16x32_bf16 v[116:119], v[172:175], v[188:191], v[116:119]
	v_mfma_f32_16x16x32_bf16 v[112:115], v[180:183], v[188:191], v[112:115]
	v_mfma_f32_16x16x32_bf16 v[100:103], v[172:175], v[196:199], v[100:103]
	v_mfma_f32_16x16x32_bf16 v[96:99], v[180:183], v[196:199], v[96:99]
	v_mfma_f32_16x16x32_bf16 v[84:87], v[172:175], v[204:207], v[84:87]
	v_mfma_f32_16x16x32_bf16 v[80:83], v[180:183], v[204:207], v[80:83]
	v_mfma_f32_16x16x32_bf16 v[68:71], v[172:175], v[212:215], v[68:71]
	v_mfma_f32_16x16x32_bf16 v[64:67], v[180:183], v[212:215], v[64:67]
	s_barrier
	s_add_i32 s53, s42, s28
	v_lshl_add_u64 v[160:161], s[20:21], 0, v[130:131]
	s_mov_b32 m0, s53
	ds_read_b128 v[184:187], v169 offset:16384
	ds_read_b128 v[188:191], v169 offset:17408
	ds_read_b128 v[192:195], v169 offset:18432
	ds_read_b128 v[196:199], v169 offset:19456
	ds_read_b128 v[200:203], v169 offset:20480
	ds_read_b128 v[204:207], v169 offset:21504
	ds_read_b128 v[208:211], v169 offset:22528
	ds_read_b128 v[212:215], v169 offset:23552
	global_load_lds_dwordx4 v[160:161], off
	s_add_i32 m0, s53, 0x2000
	s_add_u32 s54, s20, 0x160000
	v_lshl_add_u64 v[216:217], s[20:21], 0, v[134:135]
	s_addc_u32 s55, s21, 0
	s_add_i32 s53, s43, s28
	global_load_lds_dwordx4 v[216:217], off
	v_lshl_add_u64 v[218:219], s[54:55], 0, v[130:131]
	s_mov_b32 m0, s53
	v_lshl_add_u64 v[220:221], s[22:23], 0, v[132:133]
	global_load_lds_dwordx4 v[218:219], off
	v_lshl_add_u64 v[218:219], s[54:55], 0, v[134:135]
	s_add_i32 m0, s53, 0x2000
	s_nop 0
	global_load_lds_dwordx4 v[218:219], off
	v_lshl_add_u64 v[218:219], s[22:23], 0, v[128:129]
	s_mov_b32 m0, s29
	s_nop 0
	global_load_lds_dwordx4 v[218:219], off
	s_mov_b32 m0, s30
	s_nop 0
	global_load_lds_dwordx4 v[220:221], off
	s_waitcnt vmcnt(8)
	s_waitcnt lgkmcnt(0)
	s_barrier
	v_mfma_f32_16x16x32_bf16 v[60:63], v[140:143], v[184:187], v[60:63]
	v_mfma_f32_16x16x32_bf16 v[56:59], v[148:151], v[184:187], v[56:59]
	v_mfma_f32_16x16x32_bf16 v[44:47], v[140:143], v[192:195], v[44:47]
	v_mfma_f32_16x16x32_bf16 v[40:43], v[148:151], v[192:195], v[40:43]
	v_mfma_f32_16x16x32_bf16 v[28:31], v[140:143], v[200:203], v[28:31]
	v_mfma_f32_16x16x32_bf16 v[24:27], v[148:151], v[200:203], v[24:27]
	v_mfma_f32_16x16x32_bf16 v[12:15], v[140:143], v[208:211], v[12:15]
	v_mfma_f32_16x16x32_bf16 v[8:11], v[148:151], v[208:211], v[8:11]
	v_mfma_f32_16x16x32_bf16 v[60:63], v[144:147], v[188:191], v[60:63]
	v_mfma_f32_16x16x32_bf16 v[56:59], v[152:155], v[188:191], v[56:59]
	v_mfma_f32_16x16x32_bf16 v[44:47], v[144:147], v[196:199], v[44:47]
	v_mfma_f32_16x16x32_bf16 v[40:43], v[152:155], v[196:199], v[40:43]
	v_mfma_f32_16x16x32_bf16 v[28:31], v[144:147], v[204:207], v[28:31]
	v_mfma_f32_16x16x32_bf16 v[24:27], v[152:155], v[204:207], v[24:27]
	v_mfma_f32_16x16x32_bf16 v[12:15], v[144:147], v[212:215], v[12:15]
	v_mfma_f32_16x16x32_bf16 v[8:11], v[152:155], v[212:215], v[8:11]
	v_mfma_f32_16x16x32_bf16 v[52:55], v[156:159], v[184:187], v[52:55]
	v_mfma_f32_16x16x32_bf16 v[48:51], v[176:179], v[184:187], v[48:51]
	v_mfma_f32_16x16x32_bf16 v[36:39], v[156:159], v[192:195], v[36:39]
	v_mfma_f32_16x16x32_bf16 v[32:35], v[176:179], v[192:195], v[32:35]
	v_mfma_f32_16x16x32_bf16 v[20:23], v[156:159], v[200:203], v[20:23]
	v_mfma_f32_16x16x32_bf16 v[16:19], v[176:179], v[200:203], v[16:19]
	v_mfma_f32_16x16x32_bf16 v[4:7], v[156:159], v[208:211], v[4:7]
	v_mfma_f32_16x16x32_bf16 v[0:3], v[176:179], v[208:211], v[0:3]
	v_mfma_f32_16x16x32_bf16 v[52:55], v[172:175], v[188:191], v[52:55]
	v_mfma_f32_16x16x32_bf16 v[48:51], v[180:183], v[188:191], v[48:51]
	v_mfma_f32_16x16x32_bf16 v[36:39], v[172:175], v[196:199], v[36:39]
	v_mfma_f32_16x16x32_bf16 v[32:35], v[180:183], v[196:199], v[32:35]
	v_mfma_f32_16x16x32_bf16 v[20:23], v[172:175], v[204:207], v[20:23]
	v_mfma_f32_16x16x32_bf16 v[16:19], v[180:183], v[204:207], v[16:19]
	v_mfma_f32_16x16x32_bf16 v[4:7], v[172:175], v[212:215], v[4:7]
	v_mfma_f32_16x16x32_bf16 v[0:3], v[180:183], v[212:215], v[0:3]
	s_barrier
	s_add_i32 s53, 0, 0x18000
	s_add_i32 s54, 0, 0x1c000
	v_add_u32_e32 v152, s53, v166
	v_add_u32_e32 v180, s54, v166
	ds_read_b128 v[140:143], v152
	ds_read_b128 v[144:147], v152 offset:1024
	ds_read_b128 v[148:151], v152 offset:2048
	ds_read_b128 v[152:155], v152 offset:3072
	ds_read_b128 v[156:159], v180
	ds_read_b128 v[172:175], v180 offset:1024
	ds_read_b128 v[176:179], v180 offset:2048
	ds_read_b128 v[180:183], v180 offset:3072
	s_add_u32 s22, s22, 0x160000
	s_addc_u32 s23, s23, 0
	s_mov_b32 m0, s31
	v_lshl_add_u64 v[222:223], s[22:23], 0, v[128:129]
	ds_read_b128 v[184:187], v169 offset:32768
	ds_read_b128 v[188:191], v169 offset:33792
	ds_read_b128 v[192:195], v169 offset:34816
	ds_read_b128 v[196:199], v169 offset:35840
	ds_read_b128 v[200:203], v169 offset:36864
	ds_read_b128 v[204:207], v169 offset:37888
	ds_read_b128 v[208:211], v169 offset:38912
	ds_read_b128 v[212:215], v169 offset:39936
	global_load_lds_dwordx4 v[222:223], off
	v_lshl_add_u64 v[222:223], s[22:23], 0, v[132:133]
	s_mov_b32 m0, s33
	s_nop 0
	global_load_lds_dwordx4 v[222:223], off
	s_waitcnt vmcnt(8)
	s_waitcnt lgkmcnt(0)
	s_barrier
	v_mfma_f32_16x16x32_bf16 v[124:127], v[140:143], v[184:187], v[124:127]
	v_mfma_f32_16x16x32_bf16 v[120:123], v[148:151], v[184:187], v[120:123]
	v_mfma_f32_16x16x32_bf16 v[108:111], v[140:143], v[192:195], v[108:111]
	v_mfma_f32_16x16x32_bf16 v[104:107], v[148:151], v[192:195], v[104:107]
	v_mfma_f32_16x16x32_bf16 v[92:95], v[140:143], v[200:203], v[92:95]
	v_mfma_f32_16x16x32_bf16 v[88:91], v[148:151], v[200:203], v[88:91]
	v_mfma_f32_16x16x32_bf16 v[76:79], v[140:143], v[208:211], v[76:79]
	v_mfma_f32_16x16x32_bf16 v[72:75], v[148:151], v[208:211], v[72:75]
	v_mfma_f32_16x16x32_bf16 v[124:127], v[144:147], v[188:191], v[124:127]
	v_mfma_f32_16x16x32_bf16 v[120:123], v[152:155], v[188:191], v[120:123]
	v_mfma_f32_16x16x32_bf16 v[108:111], v[144:147], v[196:199], v[108:111]
	v_mfma_f32_16x16x32_bf16 v[104:107], v[152:155], v[196:199], v[104:107]
	v_mfma_f32_16x16x32_bf16 v[92:95], v[144:147], v[204:207], v[92:95]
	v_mfma_f32_16x16x32_bf16 v[88:91], v[152:155], v[204:207], v[88:91]
	v_mfma_f32_16x16x32_bf16 v[76:79], v[144:147], v[212:215], v[76:79]
	v_mfma_f32_16x16x32_bf16 v[72:75], v[152:155], v[212:215], v[72:75]
	v_mfma_f32_16x16x32_bf16 v[116:119], v[156:159], v[184:187], v[116:119]
	v_mfma_f32_16x16x32_bf16 v[112:115], v[176:179], v[184:187], v[112:115]
	v_mfma_f32_16x16x32_bf16 v[100:103], v[156:159], v[192:195], v[100:103]
	v_mfma_f32_16x16x32_bf16 v[96:99], v[176:179], v[192:195], v[96:99]
	v_mfma_f32_16x16x32_bf16 v[84:87], v[156:159], v[200:203], v[84:87]
	v_mfma_f32_16x16x32_bf16 v[80:83], v[176:179], v[200:203], v[80:83]
	v_mfma_f32_16x16x32_bf16 v[68:71], v[156:159], v[208:211], v[68:71]
	v_mfma_f32_16x16x32_bf16 v[64:67], v[176:179], v[208:211], v[64:67]
	v_mfma_f32_16x16x32_bf16 v[116:119], v[172:175], v[188:191], v[116:119]
	v_mfma_f32_16x16x32_bf16 v[112:115], v[180:183], v[188:191], v[112:115]
	v_mfma_f32_16x16x32_bf16 v[100:103], v[172:175], v[196:199], v[100:103]
	v_mfma_f32_16x16x32_bf16 v[96:99], v[180:183], v[196:199], v[96:99]
	v_mfma_f32_16x16x32_bf16 v[84:87], v[172:175], v[204:207], v[84:87]
	v_mfma_f32_16x16x32_bf16 v[80:83], v[180:183], v[204:207], v[80:83]
	v_mfma_f32_16x16x32_bf16 v[68:71], v[172:175], v[212:215], v[68:71]
	v_mfma_f32_16x16x32_bf16 v[64:67], v[180:183], v[212:215], v[64:67]
	s_barrier
	s_add_i32 s22, s53, s28
	v_lshl_add_u64 v[160:161], v[160:161], 0, s[8:9]
	s_mov_b32 m0, s22
	ds_read_b128 v[184:187], v169 offset:49152
	ds_read_b128 v[188:191], v169 offset:50176
	ds_read_b128 v[192:195], v169 offset:51200
	ds_read_b128 v[196:199], v169 offset:52224
	ds_read_b128 v[200:203], v169 offset:53248
	ds_read_b128 v[204:207], v169 offset:54272
	ds_read_b128 v[208:211], v169 offset:55296
	ds_read_b128 v[212:215], v169 offset:56320
	global_load_lds_dwordx4 v[160:161], off
	s_add_i32 m0, s22, 0x2000
	s_add_u32 s20, s20, 0x160080
	v_lshl_add_u64 v[160:161], v[216:217], 0, s[8:9]
	s_addc_u32 s21, s21, 0
	s_add_i32 s22, s54, s28
	global_load_lds_dwordx4 v[160:161], off
	v_lshl_add_u64 v[160:161], s[20:21], 0, v[130:131]
	s_mov_b32 m0, s22
	s_nop 0
	global_load_lds_dwordx4 v[160:161], off
	v_lshl_add_u64 v[160:161], s[20:21], 0, v[134:135]
	s_add_i32 m0, s22, 0x2000
	s_nop 0
	global_load_lds_dwordx4 v[160:161], off
	v_lshl_add_u64 v[160:161], v[218:219], 0, s[8:9]
	s_mov_b32 m0, s39
	s_nop 0
	global_load_lds_dwordx4 v[160:161], off
	v_lshl_add_u64 v[160:161], v[220:221], 0, s[8:9]
	s_mov_b32 m0, s40
	s_nop 0
	global_load_lds_dwordx4 v[160:161], off
	s_waitcnt vmcnt(8)
	s_waitcnt lgkmcnt(0)
	s_barrier
	v_mfma_f32_16x16x32_bf16 v[60:63], v[140:143], v[184:187], v[60:63]
	v_mfma_f32_16x16x32_bf16 v[56:59], v[148:151], v[184:187], v[56:59]
	v_mfma_f32_16x16x32_bf16 v[44:47], v[140:143], v[192:195], v[44:47]
	v_mfma_f32_16x16x32_bf16 v[40:43], v[148:151], v[192:195], v[40:43]
	v_mfma_f32_16x16x32_bf16 v[28:31], v[140:143], v[200:203], v[28:31]
	v_mfma_f32_16x16x32_bf16 v[24:27], v[148:151], v[200:203], v[24:27]
	v_mfma_f32_16x16x32_bf16 v[12:15], v[140:143], v[208:211], v[12:15]
	v_mfma_f32_16x16x32_bf16 v[8:11], v[148:151], v[208:211], v[8:11]
	v_mfma_f32_16x16x32_bf16 v[60:63], v[144:147], v[188:191], v[60:63]
	v_mfma_f32_16x16x32_bf16 v[56:59], v[152:155], v[188:191], v[56:59]
	v_mfma_f32_16x16x32_bf16 v[44:47], v[144:147], v[196:199], v[44:47]
	v_mfma_f32_16x16x32_bf16 v[40:43], v[152:155], v[196:199], v[40:43]
	v_mfma_f32_16x16x32_bf16 v[28:31], v[144:147], v[204:207], v[28:31]
	v_mfma_f32_16x16x32_bf16 v[24:27], v[152:155], v[204:207], v[24:27]
	v_mfma_f32_16x16x32_bf16 v[12:15], v[144:147], v[212:215], v[12:15]
	v_mfma_f32_16x16x32_bf16 v[8:11], v[152:155], v[212:215], v[8:11]
	v_mfma_f32_16x16x32_bf16 v[52:55], v[156:159], v[184:187], v[52:55]
	v_mfma_f32_16x16x32_bf16 v[48:51], v[176:179], v[184:187], v[48:51]
	v_mfma_f32_16x16x32_bf16 v[36:39], v[156:159], v[192:195], v[36:39]
	v_mfma_f32_16x16x32_bf16 v[32:35], v[176:179], v[192:195], v[32:35]
	v_mfma_f32_16x16x32_bf16 v[20:23], v[156:159], v[200:203], v[20:23]
	v_mfma_f32_16x16x32_bf16 v[16:19], v[176:179], v[200:203], v[16:19]
	v_mfma_f32_16x16x32_bf16 v[4:7], v[156:159], v[208:211], v[4:7]
	v_mfma_f32_16x16x32_bf16 v[0:3], v[176:179], v[208:211], v[0:3]
	v_mfma_f32_16x16x32_bf16 v[52:55], v[172:175], v[188:191], v[52:55]
	v_mfma_f32_16x16x32_bf16 v[48:51], v[180:183], v[188:191], v[48:51]
	v_mfma_f32_16x16x32_bf16 v[36:39], v[172:175], v[196:199], v[36:39]
	v_mfma_f32_16x16x32_bf16 v[32:35], v[180:183], v[196:199], v[32:35]
	v_mfma_f32_16x16x32_bf16 v[20:23], v[172:175], v[204:207], v[20:23]
	v_mfma_f32_16x16x32_bf16 v[16:19], v[180:183], v[204:207], v[16:19]
	v_mfma_f32_16x16x32_bf16 v[4:7], v[172:175], v[212:215], v[4:7]
	v_mfma_f32_16x16x32_bf16 v[0:3], v[180:183], v[212:215], v[0:3]
	s_barrier
	s_add_i32 s52, s52, 2
	s_add_u32 s0, s0, 0x100
	s_addc_u32 s1, s1, 0
	s_add_u32 s50, s50, 0x100
	s_addc_u32 s51, s51, 0
	s_cmpk_gt_u32 s52, 0x55
	s_cbranch_scc0 .LBB0_1449
	s_setprio 0
	s_and_b64 vcc, exec, s[10:11]
	s_cbranch_vccz .LBB0_1452
	s_barrier
